# v24: v22 plus nt stores for the RG-LRU gate GEMM outputs
# speedup vs baseline: 1.0036x; 1.0036x over previous
.LBB0_1645:
	s_add_u32 s57, s48, s56
	s_addc_u32 s58, s49, 0
	s_add_u32 s59, s57, 0x100
	s_addc_u32 s60, s58, 0
	s_and_b64 s[0:1], s[54:55], exec
	s_cselect_b32 s61, s43, s60
	s_cselect_b32 s60, s83, s59
	s_add_u32 s0, s14, s56
	s_addc_u32 s1, s15, 0
	s_add_u32 s56, s0, 0x100
	s_addc_u32 s59, s1, 0
	s_and_b64 s[0:1], s[54:55], exec
	s_cselect_b32 s63, s41, s59
	s_cselect_b32 s62, s94, s56
	s_add_u32 s64, s57, 0x40080
	s_addc_u32 s65, s58, 0
	s_add_i32 s0, s85, s37
	s_add_i32 m0, s39, 0xc000
	s_add_i32 s71, s39, 0xe000
	s_add_i32 s70, s0, 0x2000
	s_add_u32 s58, s62, 0x10000
	s_addc_u32 s59, s63, 0
	s_add_i32 s1, s4, s37
	ds_read_b128 v[26:29], v225
	ds_read_b128 v[30:33], v225 offset:1024
	ds_read_b128 v[42:45], v225 offset:2048
	ds_read_b128 v[46:49], v225 offset:3072
	s_add_i32 s96, s1, 0x2000
	s_add_i32 s81, 0, 0x18000
	s_add_u32 s56, s60, 0x40000
	s_addc_u32 s57, s61, 0
	s_add_i32 s78, s81, s37
	s_add_i32 s79, 0, 0x1c000
	s_add_i32 s80, s78, 0x2000
	s_add_u32 s54, s62, 0x10080
	s_addc_u32 s55, s63, 0
	s_add_i32 vcc_hi, s79, s37
	s_add_i32 vcc_lo, vcc_hi, 0x2000
	v_lshl_add_u64 v[190:191], s[64:65], 0, v[160:161]
	ds_read_b128 v[146:149], v226
	ds_read_b128 v[150:153], v226 offset:1024
	ds_read_b128 v[166:169], v226 offset:2048
	ds_read_b128 v[170:173], v226 offset:3072
	ds_read_b128 v[174:177], v226 offset:4096
	ds_read_b128 v[178:181], v226 offset:5120
	ds_read_b128 v[182:185], v226 offset:6144
	ds_read_b128 v[186:189], v226 offset:7168
	global_load_lds_dwordx4 v[190:191], off
	v_lshl_add_u64 v[190:191], s[64:65], 0, v[156:157]
	s_mov_b32 m0, s71
	s_nop 0
	global_load_lds_dwordx4 v[190:191], off
	s_waitcnt lgkmcnt(8)
	s_waitcnt vmcnt(10)
	s_barrier
	s_waitcnt lgkmcnt(0)
	s_waitcnt lgkmcnt(0)
	v_mfma_f32_16x16x32_bf16 v[142:145], v[26:29], v[146:149], v[142:145]
	v_mfma_f32_16x16x32_bf16 v[134:137], v[42:45], v[146:149], v[134:137]
	v_mfma_f32_16x16x32_bf16 v[126:129], v[26:29], v[166:169], v[126:129]
	v_mfma_f32_16x16x32_bf16 v[118:121], v[42:45], v[166:169], v[118:121]
	v_mfma_f32_16x16x32_bf16 v[110:113], v[26:29], v[174:177], v[110:113]
	v_mfma_f32_16x16x32_bf16 v[102:105], v[42:45], v[174:177], v[102:105]
	v_mfma_f32_16x16x32_bf16 v[94:97], v[26:29], v[182:185], v[94:97]
	v_mfma_f32_16x16x32_bf16 v[86:89], v[42:45], v[182:185], v[86:89]
	v_mfma_f32_16x16x32_bf16 v[142:145], v[30:33], v[150:153], v[142:145]
	v_mfma_f32_16x16x32_bf16 v[134:137], v[46:49], v[150:153], v[134:137]
	v_mfma_f32_16x16x32_bf16 v[126:129], v[30:33], v[170:173], v[126:129]
	v_mfma_f32_16x16x32_bf16 v[118:121], v[46:49], v[170:173], v[118:121]
	v_mfma_f32_16x16x32_bf16 v[110:113], v[30:33], v[178:181], v[110:113]
	v_mfma_f32_16x16x32_bf16 v[102:105], v[46:49], v[178:181], v[102:105]
	v_mfma_f32_16x16x32_bf16 v[94:97], v[30:33], v[186:189], v[94:97]
	v_mfma_f32_16x16x32_bf16 v[86:89], v[46:49], v[186:189], v[86:89]
	s_barrier
	s_mov_b32 m0, s0
	v_lshl_add_u64 v[206:207], s[62:63], 0, v[158:159]
	ds_read_b128 v[190:193], v227
	ds_read_b128 v[194:197], v227 offset:1024
	ds_read_b128 v[198:201], v227 offset:2048
	ds_read_b128 v[202:205], v227 offset:3072
	global_load_lds_dwordx4 v[206:207], off
	v_lshl_add_u64 v[208:209], s[62:63], 0, v[154:155]
	s_mov_b32 m0, s70
	s_nop 0
	global_load_lds_dwordx4 v[208:209], off
	s_waitcnt vmcnt(10)
	s_barrier
	s_waitcnt lgkmcnt(0)
	s_waitcnt lgkmcnt(0)
	v_mfma_f32_16x16x32_bf16 v[138:141], v[190:193], v[146:149], v[138:141]
	v_mfma_f32_16x16x32_bf16 v[130:133], v[198:201], v[146:149], v[130:133]
	v_mfma_f32_16x16x32_bf16 v[122:125], v[190:193], v[166:169], v[122:125]
	v_mfma_f32_16x16x32_bf16 v[114:117], v[198:201], v[166:169], v[114:117]
	v_mfma_f32_16x16x32_bf16 v[106:109], v[190:193], v[174:177], v[106:109]
	v_mfma_f32_16x16x32_bf16 v[98:101], v[198:201], v[174:177], v[98:101]
	v_mfma_f32_16x16x32_bf16 v[90:93], v[190:193], v[182:185], v[90:93]
	v_mfma_f32_16x16x32_bf16 v[82:85], v[198:201], v[182:185], v[82:85]
	v_mfma_f32_16x16x32_bf16 v[138:141], v[194:197], v[150:153], v[138:141]
	v_mfma_f32_16x16x32_bf16 v[130:133], v[202:205], v[150:153], v[130:133]
	v_mfma_f32_16x16x32_bf16 v[122:125], v[194:197], v[170:173], v[122:125]
	v_mfma_f32_16x16x32_bf16 v[114:117], v[202:205], v[170:173], v[114:117]
	v_mfma_f32_16x16x32_bf16 v[106:109], v[194:197], v[178:181], v[106:109]
	v_mfma_f32_16x16x32_bf16 v[98:101], v[202:205], v[178:181], v[98:101]
	v_mfma_f32_16x16x32_bf16 v[90:93], v[194:197], v[186:189], v[90:93]
	v_mfma_f32_16x16x32_bf16 v[82:85], v[202:205], v[186:189], v[82:85]
	s_mov_b32 m0, s39
	v_lshl_add_u64 v[210:211], s[60:61], 0, v[160:161]
	s_barrier
	ds_read_b128 v[146:149], v226 offset:16384
	ds_read_b128 v[150:153], v226 offset:17408
	ds_read_b128 v[166:169], v226 offset:18432
	ds_read_b128 v[170:173], v226 offset:19456
	ds_read_b128 v[174:177], v226 offset:20480
	ds_read_b128 v[178:181], v226 offset:21504
	ds_read_b128 v[182:185], v226 offset:22528
	ds_read_b128 v[186:189], v226 offset:23552
	global_load_lds_dwordx4 v[210:211], off
	v_lshl_add_u64 v[212:213], s[60:61], 0, v[156:157]
	s_mov_b32 m0, s53
	s_nop 0
	global_load_lds_dwordx4 v[212:213], off
	s_waitcnt vmcnt(10)
	s_barrier
	s_waitcnt lgkmcnt(0)
	s_waitcnt lgkmcnt(0)
	v_mfma_f32_16x16x32_bf16 v[78:81], v[26:29], v[146:149], v[78:81]
	v_mfma_f32_16x16x32_bf16 v[70:73], v[42:45], v[146:149], v[70:73]
	v_mfma_f32_16x16x32_bf16 v[62:65], v[26:29], v[166:169], v[62:65]
	v_mfma_f32_16x16x32_bf16 v[54:57], v[42:45], v[166:169], v[54:57]
	v_mfma_f32_16x16x32_bf16 v[38:41], v[26:29], v[174:177], v[38:41]
	v_mfma_f32_16x16x32_bf16 v[22:25], v[42:45], v[174:177], v[22:25]
	v_mfma_f32_16x16x32_bf16 v[14:17], v[26:29], v[182:185], v[14:17]
	v_mfma_f32_16x16x32_bf16 v[6:9], v[42:45], v[182:185], v[6:9]
	v_mfma_f32_16x16x32_bf16 v[78:81], v[30:33], v[150:153], v[78:81]
	v_mfma_f32_16x16x32_bf16 v[70:73], v[46:49], v[150:153], v[70:73]
	v_mfma_f32_16x16x32_bf16 v[62:65], v[30:33], v[170:173], v[62:65]
	v_mfma_f32_16x16x32_bf16 v[54:57], v[46:49], v[170:173], v[54:57]
	v_mfma_f32_16x16x32_bf16 v[38:41], v[30:33], v[178:181], v[38:41]
	v_mfma_f32_16x16x32_bf16 v[22:25], v[46:49], v[178:181], v[22:25]
	v_mfma_f32_16x16x32_bf16 v[14:17], v[30:33], v[186:189], v[14:17]
	v_mfma_f32_16x16x32_bf16 v[6:9], v[46:49], v[186:189], v[6:9]
	s_barrier
	s_mov_b32 m0, s1
	v_lshl_add_u64 v[26:27], s[58:59], 0, v[158:159]
	global_load_lds_dwordx4 v[26:27], off
	v_lshl_add_u64 v[26:27], s[58:59], 0, v[154:155]
	s_mov_b32 m0, s96
	s_nop 0
	global_load_lds_dwordx4 v[26:27], off
	s_waitcnt vmcnt(10)
	s_barrier
	v_mfma_f32_16x16x32_bf16 v[34:37], v[190:193], v[174:177], v[34:37]
	v_mfma_f32_16x16x32_bf16 v[18:21], v[198:201], v[174:177], v[18:21]
	v_mfma_f32_16x16x32_bf16 v[10:13], v[190:193], v[182:185], v[10:13]
	v_mfma_f32_16x16x32_bf16 v[2:5], v[198:201], v[182:185], v[2:5]
	v_mfma_f32_16x16x32_bf16 v[26:29], v[190:193], v[146:149], v[74:77]
	v_mfma_f32_16x16x32_bf16 v[30:33], v[198:201], v[146:149], v[66:69]
	v_mfma_f32_16x16x32_bf16 v[42:45], v[190:193], v[166:169], v[58:61]
	v_mfma_f32_16x16x32_bf16 v[46:49], v[198:201], v[166:169], v[50:53]
	v_mfma_f32_16x16x32_bf16 v[34:37], v[194:197], v[178:181], v[34:37]
	v_mfma_f32_16x16x32_bf16 v[18:21], v[202:205], v[178:181], v[18:21]
	v_mfma_f32_16x16x32_bf16 v[10:13], v[194:197], v[186:189], v[10:13]
	v_mfma_f32_16x16x32_bf16 v[2:5], v[202:205], v[186:189], v[2:5]
	v_mfma_f32_16x16x32_bf16 v[26:29], v[194:197], v[150:153], v[26:29]
	v_mfma_f32_16x16x32_bf16 v[30:33], v[202:205], v[150:153], v[30:33]
	v_mfma_f32_16x16x32_bf16 v[42:45], v[194:197], v[170:173], v[42:45]
	v_mfma_f32_16x16x32_bf16 v[46:49], v[202:205], v[170:173], v[46:49]
	v_add_u32_e32 v74, s81, v224
	s_barrier
	ds_read_b128 v[50:53], v74
	ds_read_b128 v[58:61], v74 offset:1024
	ds_read_b128 v[66:69], v74 offset:2048
	ds_read_b128 v[74:77], v74 offset:3072
	s_mov_b32 m0, s66
	v_lshl_add_u64 v[190:191], s[56:57], 0, v[160:161]
	ds_read_b128 v[146:149], v226 offset:32768
	ds_read_b128 v[150:153], v226 offset:33792
	ds_read_b128 v[166:169], v226 offset:34816
	ds_read_b128 v[170:173], v226 offset:35840
	ds_read_b128 v[174:177], v226 offset:36864
	ds_read_b128 v[178:181], v226 offset:37888
	ds_read_b128 v[182:185], v226 offset:38912
	ds_read_b128 v[186:189], v226 offset:39936
	global_load_lds_dwordx4 v[190:191], off
	v_lshl_add_u64 v[190:191], s[56:57], 0, v[156:157]
	s_mov_b32 m0, s67
	s_nop 0
	global_load_lds_dwordx4 v[190:191], off
	s_waitcnt lgkmcnt(8)
	s_waitcnt vmcnt(10)
	s_barrier
	s_waitcnt lgkmcnt(0)
	s_waitcnt lgkmcnt(0)
	v_mfma_f32_16x16x32_bf16 v[142:145], v[50:53], v[146:149], v[142:145]
	v_mfma_f32_16x16x32_bf16 v[134:137], v[66:69], v[146:149], v[134:137]
	v_mfma_f32_16x16x32_bf16 v[126:129], v[50:53], v[166:169], v[126:129]
	v_mfma_f32_16x16x32_bf16 v[118:121], v[66:69], v[166:169], v[118:121]
	v_mfma_f32_16x16x32_bf16 v[110:113], v[50:53], v[174:177], v[110:113]
	v_mfma_f32_16x16x32_bf16 v[102:105], v[66:69], v[174:177], v[102:105]
	v_mfma_f32_16x16x32_bf16 v[94:97], v[50:53], v[182:185], v[94:97]
	v_mfma_f32_16x16x32_bf16 v[86:89], v[66:69], v[182:185], v[86:89]
	v_mfma_f32_16x16x32_bf16 v[142:145], v[58:61], v[150:153], v[142:145]
	v_mfma_f32_16x16x32_bf16 v[134:137], v[74:77], v[150:153], v[134:137]
	v_mfma_f32_16x16x32_bf16 v[126:129], v[58:61], v[170:173], v[126:129]
	v_mfma_f32_16x16x32_bf16 v[118:121], v[74:77], v[170:173], v[118:121]
	v_mfma_f32_16x16x32_bf16 v[110:113], v[58:61], v[178:181], v[110:113]
	v_mfma_f32_16x16x32_bf16 v[102:105], v[74:77], v[178:181], v[102:105]
	v_mfma_f32_16x16x32_bf16 v[94:97], v[58:61], v[186:189], v[94:97]
	v_mfma_f32_16x16x32_bf16 v[86:89], v[74:77], v[186:189], v[86:89]
	s_barrier
	s_mov_b32 m0, s78
	v_add_u32_e32 v202, s79, v224
	v_lshl_add_u64 v[206:207], v[206:207], 0, s[26:27]
	ds_read_b128 v[190:193], v202
	ds_read_b128 v[194:197], v202 offset:1024
	ds_read_b128 v[198:201], v202 offset:2048
	ds_read_b128 v[202:205], v202 offset:3072
	global_load_lds_dwordx4 v[206:207], off
	v_lshl_add_u64 v[206:207], v[208:209], 0, s[26:27]
	s_mov_b32 m0, s80
	s_nop 0
	global_load_lds_dwordx4 v[206:207], off
	s_waitcnt vmcnt(10)
	s_barrier
	s_waitcnt lgkmcnt(0)
	s_waitcnt lgkmcnt(0)
	v_mfma_f32_16x16x32_bf16 v[138:141], v[190:193], v[146:149], v[138:141]
	v_mfma_f32_16x16x32_bf16 v[130:133], v[198:201], v[146:149], v[130:133]
	v_mfma_f32_16x16x32_bf16 v[122:125], v[190:193], v[166:169], v[122:125]
	v_mfma_f32_16x16x32_bf16 v[114:117], v[198:201], v[166:169], v[114:117]
	v_mfma_f32_16x16x32_bf16 v[106:109], v[190:193], v[174:177], v[106:109]
	v_mfma_f32_16x16x32_bf16 v[98:101], v[198:201], v[174:177], v[98:101]
	v_mfma_f32_16x16x32_bf16 v[90:93], v[190:193], v[182:185], v[90:93]
	v_mfma_f32_16x16x32_bf16 v[82:85], v[198:201], v[182:185], v[82:85]
	v_mfma_f32_16x16x32_bf16 v[138:141], v[194:197], v[150:153], v[138:141]
	v_mfma_f32_16x16x32_bf16 v[130:133], v[202:205], v[150:153], v[130:133]
	v_mfma_f32_16x16x32_bf16 v[122:125], v[194:197], v[170:173], v[122:125]
	v_mfma_f32_16x16x32_bf16 v[114:117], v[202:205], v[170:173], v[114:117]
	v_mfma_f32_16x16x32_bf16 v[106:109], v[194:197], v[178:181], v[106:109]
	v_mfma_f32_16x16x32_bf16 v[98:101], v[202:205], v[178:181], v[98:101]
	v_mfma_f32_16x16x32_bf16 v[90:93], v[194:197], v[186:189], v[90:93]
	v_mfma_f32_16x16x32_bf16 v[82:85], v[202:205], v[186:189], v[82:85]
	s_mov_b32 m0, s6
	v_lshl_add_u64 v[206:207], v[210:211], 0, s[26:27]
	s_barrier
	ds_read_b128 v[146:149], v226 offset:49152
	ds_read_b128 v[150:153], v226 offset:50176
	ds_read_b128 v[166:169], v226 offset:51200
	ds_read_b128 v[170:173], v226 offset:52224
	ds_read_b128 v[174:177], v226 offset:53248
	ds_read_b128 v[178:181], v226 offset:54272
	ds_read_b128 v[182:185], v226 offset:55296
	ds_read_b128 v[186:189], v226 offset:56320
	global_load_lds_dwordx4 v[206:207], off
	v_lshl_add_u64 v[206:207], v[212:213], 0, s[26:27]
	s_mov_b32 m0, s7
	s_nop 0
	global_load_lds_dwordx4 v[206:207], off
	s_waitcnt vmcnt(10)
	s_barrier
	s_waitcnt lgkmcnt(0)
	s_waitcnt lgkmcnt(0)
	v_mfma_f32_16x16x32_bf16 v[78:81], v[50:53], v[146:149], v[78:81]
	v_mfma_f32_16x16x32_bf16 v[70:73], v[66:69], v[146:149], v[70:73]
	v_mfma_f32_16x16x32_bf16 v[62:65], v[50:53], v[166:169], v[62:65]
	v_mfma_f32_16x16x32_bf16 v[54:57], v[66:69], v[166:169], v[54:57]
	v_mfma_f32_16x16x32_bf16 v[38:41], v[50:53], v[174:177], v[38:41]
	v_mfma_f32_16x16x32_bf16 v[22:25], v[66:69], v[174:177], v[22:25]
	v_mfma_f32_16x16x32_bf16 v[14:17], v[50:53], v[182:185], v[14:17]
	v_mfma_f32_16x16x32_bf16 v[6:9], v[66:69], v[182:185], v[6:9]
	v_mfma_f32_16x16x32_bf16 v[78:81], v[58:61], v[150:153], v[78:81]
	v_mfma_f32_16x16x32_bf16 v[70:73], v[74:77], v[150:153], v[70:73]
	v_mfma_f32_16x16x32_bf16 v[62:65], v[58:61], v[170:173], v[62:65]
	v_mfma_f32_16x16x32_bf16 v[54:57], v[74:77], v[170:173], v[54:57]
	v_mfma_f32_16x16x32_bf16 v[38:41], v[58:61], v[178:181], v[38:41]
	v_mfma_f32_16x16x32_bf16 v[22:25], v[74:77], v[178:181], v[22:25]
	v_mfma_f32_16x16x32_bf16 v[14:17], v[58:61], v[186:189], v[14:17]
	v_mfma_f32_16x16x32_bf16 v[6:9], v[74:77], v[186:189], v[6:9]
	s_barrier
	s_mov_b32 m0, vcc_hi
	v_lshl_add_u64 v[50:51], s[54:55], 0, v[158:159]
	global_load_lds_dwordx4 v[50:51], off
	v_lshl_add_u64 v[50:51], s[54:55], 0, v[154:155]
	s_mov_b32 m0, vcc_lo
	s_nop 0
	global_load_lds_dwordx4 v[50:51], off
	s_waitcnt vmcnt(10)
	s_barrier
	v_mfma_f32_16x16x32_bf16 v[26:29], v[190:193], v[146:149], v[26:29]
	v_mfma_f32_16x16x32_bf16 v[74:77], v[194:197], v[150:153], v[26:29]
	v_mfma_f32_16x16x32_bf16 v[26:29], v[198:201], v[146:149], v[30:33]
	v_mfma_f32_16x16x32_bf16 v[66:69], v[202:205], v[150:153], v[26:29]
	v_mfma_f32_16x16x32_bf16 v[26:29], v[190:193], v[166:169], v[42:45]
	v_mfma_f32_16x16x32_bf16 v[58:61], v[194:197], v[170:173], v[26:29]
	v_mfma_f32_16x16x32_bf16 v[26:29], v[198:201], v[166:169], v[46:49]
	v_mfma_f32_16x16x32_bf16 v[50:53], v[202:205], v[170:173], v[26:29]
	v_mfma_f32_16x16x32_bf16 v[26:29], v[190:193], v[174:177], v[34:37]
	v_mfma_f32_16x16x32_bf16 v[18:21], v[198:201], v[174:177], v[18:21]
	v_mfma_f32_16x16x32_bf16 v[10:13], v[190:193], v[182:185], v[10:13]
	v_mfma_f32_16x16x32_bf16 v[2:5], v[198:201], v[182:185], v[2:5]
	v_mfma_f32_16x16x32_bf16 v[34:37], v[194:197], v[178:181], v[26:29]
	v_mfma_f32_16x16x32_bf16 v[18:21], v[202:205], v[178:181], v[18:21]
	v_mfma_f32_16x16x32_bf16 v[10:13], v[194:197], v[186:189], v[10:13]
	v_mfma_f32_16x16x32_bf16 v[2:5], v[202:205], v[186:189], v[2:5]
	s_movk_i32 s56, 0x100
	s_andn2_b64 vcc, exec, s[50:51]
	s_mov_b64 s[54:55], -1
	s_mov_b64 s[50:51], 0
	s_barrier
	s_cbranch_vccz .LBB0_1645
	s_lshl_b32 s0, s82, 7
	s_and_b32 s1, s0, 0x380
	v_mov_b32_e32 v167, v222
	v_mov_b32_e32 v26, v223
	s_or_b32 s1, s1, s11
	s_cmp_lt_u32 s82, 8
	v_lshl_add_u32 v166, v26, 3, s1
	s_mov_b32 s1, 0x32100000
	s_cselect_b32 s1, s1, 0x1a100000
	s_cselect_b32 s49, s9, s17
	s_cselect_b32 s48, s8, s16
	s_add_u32 s50, s18, s1
	s_addc_u32 s51, s19, 0
	s_and_b32 s0, s0, 0xfffffc00
	v_add_u32_e32 v26, s0, v166
	s_load_dwordx2 s[0:1], s[20:21], 0x78
	v_ashrrev_i32_e32 v27, 31, v26
	v_readlane_b32 s56, v254, 5
	v_lshlrev_b64 v[146:147], 2, v[26:27]
	v_readlane_b32 s57, v254, 6
	v_readlane_b32 s58, v254, 7
	v_readlane_b32 s59, v254, 8
	s_waitcnt lgkmcnt(0)
	v_lshl_add_u64 v[26:27], s[0:1], 0, v[146:147]
	v_lshl_add_u64 v[42:43], s[56:57], 0, v[146:147]
	v_lshl_add_u64 v[150:151], s[58:59], 0, v[146:147]
	global_load_dwordx4 v[30:33], v[26:27], off offset:16
	global_load_dwordx4 v[46:49], v[26:27], off
	s_nop 0
	global_load_dwordx4 v[26:29], v[42:43], off offset:16
	s_nop 0
	global_load_dwordx4 v[42:45], v[42:43], off
	s_nop 0
	global_load_dwordx4 v[146:149], v[150:151], off offset:16
	s_nop 0
	global_load_dwordx4 v[150:153], v[150:151], off
	s_lshl_b32 s0, s52, 8
	s_add_i32 s0, s0, s10
	s_waitcnt vmcnt(0)
	v_add_f32_e32 v134, v134, v30
	v_add_f32_e32 v142, v142, v46
	v_add_f32_e32 v138, v138, v42
	v_max_f32_e32 v168, v150, v150
	v_mul_f32_e64 v150, |v150|, s5
	v_exp_f32_e32 v232, v150
	v_mul_f32_e32 v138, 0xbfb8aa3b, v138
	v_exp_f32_e32 v138, v138
	v_mul_f32_e32 v142, 0xbfb8aa3b, v142
	v_add_f32_e32 v172, 1.0, v232
	v_add_f32_e32 v150, -1.0, v172
	v_sub_f32_e32 v169, v150, v172
	v_add_f32_e32 v169, 1.0, v169
	v_sub_f32_e32 v150, v232, v150
	v_add_f32_e32 v174, v150, v169
	v_max_f32_e32 v150, v151, v151
	v_min_f32_e32 v169, 0, v150
	v_mul_f32_e64 v150, |v151|, s5
	v_exp_f32_e32 v233, v150
	v_cvt_f64_f32_e32 v[170:171], v172
	v_frexp_exp_i32_f64_e32 v170, v[170:171]
	v_frexp_mant_f32_e32 v173, v172
	v_add_f32_e32 v171, 1.0, v233
	v_add_f32_e32 v150, -1.0, v171
	v_sub_f32_e32 v151, v150, v171
	v_add_f32_e32 v151, 1.0, v151
	v_sub_f32_e32 v150, v233, v150
	v_add_f32_e32 v175, v150, v151
	v_frexp_mant_f32_e32 v176, v171
	v_cvt_f64_f32_e32 v[150:151], v171
	v_cmp_gt_f32_e32 vcc, s72, v173
	v_frexp_exp_i32_f64_e32 v150, v[150:151]
	v_cmp_gt_f32_e64 s[14:15], s72, v176
	v_subbrev_co_u32_e32 v176, vcc, 0, v170, vcc
	s_nop 0
	v_subbrev_co_u32_e64 v173, s[14:15], 0, v150, s[14:15]
	v_sub_u32_e32 v151, 0, v176
	v_ldexp_f32 v150, v172, v151
	v_sub_u32_e32 v172, 0, v173
	v_ldexp_f32 v170, v174, v151
	v_ldexp_f32 v151, v171, v172
	v_ldexp_f32 v171, v175, v172
	v_pk_add_f32 v[174:175], v[150:151], 1.0 op_sel_hi:[1,0]
	v_pk_add_f32 v[184:185], v[150:151], -1.0 op_sel_hi:[1,0]
	v_pk_add_f32 v[178:179], v[174:175], -1.0 op_sel_hi:[1,0]
	v_pk_add_f32 v[186:187], v[184:185], 1.0 op_sel_hi:[1,0]
	v_pk_add_f32 v[178:179], v[150:151], v[178:179] neg_lo:[0,1] neg_hi:[0,1]
	v_pk_add_f32 v[150:151], v[150:151], v[186:187] neg_lo:[0,1] neg_hi:[0,1]
	v_pk_add_f32 v[178:179], v[170:171], v[178:179]
	v_pk_add_f32 v[150:151], v[170:171], v[150:151]
	v_pk_add_f32 v[180:181], v[174:175], v[178:179]
	v_pk_add_f32 v[170:171], v[184:185], v[150:151]
	v_rcp_f32_e32 v182, v180
	v_rcp_f32_e32 v183, v181
	v_pk_add_f32 v[174:175], v[180:181], v[174:175] neg_lo:[0,1] neg_hi:[0,1]
	v_pk_add_f32 v[184:185], v[170:171], v[184:185] neg_lo:[0,1] neg_hi:[0,1]
	v_pk_add_f32 v[174:175], v[178:179], v[174:175] neg_lo:[0,1] neg_hi:[0,1]
	v_pk_mul_f32 v[186:187], v[170:171], v[182:183]
	v_pk_add_f32 v[150:151], v[150:151], v[184:185] neg_lo:[0,1] neg_hi:[0,1]
	v_pk_mul_f32 v[178:179], v[180:181], v[186:187]
	s_mov_b32 s14, 0x3ecc95a3
	v_pk_fma_f32 v[184:185], v[186:187], v[180:181], v[178:179] neg_lo:[0,0,1] neg_hi:[0,0,1]
	v_cvt_f32_i32_e32 v177, v173
	v_pk_fma_f32 v[184:185], v[186:187], v[174:175], v[184:185]
	v_cvt_f32_i32_e32 v176, v176
	v_pk_add_f32 v[188:189], v[178:179], v[184:185]
	v_add_f32_e32 v138, 1.0, v138
	v_pk_add_f32 v[190:191], v[170:171], v[188:189] neg_lo:[0,1] neg_hi:[0,1]
	v_pk_add_f32 v[178:179], v[188:189], v[178:179] neg_lo:[0,1] neg_hi:[0,1]
	v_pk_add_f32 v[170:171], v[170:171], v[190:191] neg_lo:[0,1] neg_hi:[0,1]
	v_rcp_f32_e32 v249, v138
	v_pk_add_f32 v[170:171], v[170:171], v[188:189] neg_lo:[0,1] neg_hi:[0,1]
	v_add_f32_e32 v138, v143, v47
	v_pk_add_f32 v[150:151], v[150:151], v[170:171]
	v_pk_add_f32 v[170:171], v[178:179], v[184:185] neg_lo:[0,1] neg_hi:[0,1]
	v_mul_f32_e32 v138, 0xbfb8aa3b, v138
	v_pk_add_f32 v[150:151], v[170:171], v[150:151]
	v_exp_f32_e32 v138, v138
	v_pk_add_f32 v[170:171], v[190:191], v[150:151]
	v_exp_f32_e32 v142, v142
	v_pk_mul_f32 v[178:179], v[182:183], v[170:171]
	v_pk_add_f32 v[190:191], v[190:191], v[170:171] neg_lo:[0,1] neg_hi:[0,1]
	v_pk_mul_f32 v[184:185], v[180:181], v[178:179]
	v_pk_add_f32 v[150:151], v[150:151], v[190:191]
	v_pk_fma_f32 v[180:181], v[178:179], v[180:181], v[184:185] neg_lo:[0,0,1] neg_hi:[0,0,1]
	v_pk_add_f32 v[196:197], v[186:187], v[178:179]
	v_pk_fma_f32 v[174:175], v[178:179], v[174:175], v[180:181]
	v_add_f32_e32 v138, 1.0, v138
	v_pk_add_f32 v[180:181], v[184:185], v[174:175]
	v_rcp_f32_e32 v143, v138
	v_pk_add_f32 v[192:193], v[170:171], v[180:181] neg_lo:[0,1] neg_hi:[0,1]
	v_pk_add_f32 v[188:189], v[180:181], v[184:185] neg_lo:[0,1] neg_hi:[0,1]
	v_pk_add_f32 v[194:195], v[170:171], v[192:193] neg_lo:[0,1] neg_hi:[0,1]
	v_mov_b32_e32 v170, v181
	v_mov_b32_e32 v184, v185
	v_mov_b32_e32 v185, v193
	v_pk_add_f32 v[194:195], v[194:195], v[180:181] neg_lo:[0,1] neg_hi:[0,1]
	v_pk_add_f32 v[170:171], v[170:171], v[184:185] neg_lo:[0,1] neg_hi:[0,1]
	v_mov_b32_e32 v180, v175
	v_pk_add_f32 v[170:171], v[170:171], v[180:181] neg_lo:[0,1] neg_hi:[0,1]
	v_pk_add_f32 v[188:189], v[188:189], v[174:175] neg_lo:[0,1] neg_hi:[0,1]
	v_mov_b32_e32 v195, v171
	v_pk_add_f32 v[150:151], v[150:151], v[194:195]
	v_mov_b32_e32 v189, v170
	v_pk_add_f32 v[150:151], v[188:189], v[150:151]
	v_pk_add_f32 v[170:171], v[196:197], v[186:187] neg_lo:[0,1] neg_hi:[0,1]
	v_pk_add_f32 v[150:151], v[192:193], v[150:151]
	v_pk_add_f32 v[170:171], v[178:179], v[170:171] neg_lo:[0,1] neg_hi:[0,1]
	v_pk_mul_f32 v[150:151], v[182:183], v[150:151]
	v_pk_mul_f32 v[182:183], v[176:177], s[34:35] op_sel_hi:[1,0]
	v_pk_add_f32 v[150:151], v[170:171], v[150:151]
	v_pk_fma_f32 v[184:185], v[176:177], s[34:35], v[182:183] op_sel_hi:[1,0,1] neg_lo:[0,0,1] neg_hi:[0,0,1]
	v_pk_add_f32 v[174:175], v[196:197], v[150:151]
	v_pk_fma_f32 v[184:185], v[176:177], s[36:37], v[184:185] op_sel_hi:[1,0,1]
	v_pk_add_f32 v[170:171], v[174:175], v[196:197] neg_lo:[0,1] neg_hi:[0,1]
	v_pk_mul_f32 v[178:179], v[174:175], v[174:175]
	v_pk_add_f32 v[170:171], v[150:151], v[170:171] neg_lo:[0,1] neg_hi:[0,1]
	v_mov_b64_e32 v[150:151], s[14:15]
	v_pk_fma_f32 v[180:181], v[178:179], s[28:29], v[150:151] op_sel_hi:[1,0,0]
	v_ldexp_f32 v172, v174, 1
	v_pk_fma_f32 v[180:181], v[178:179], v[180:181], s[30:31] op_sel_hi:[1,1,0]
	v_ldexp_f32 v173, v175, 1
	v_pk_mul_f32 v[174:175], v[174:175], v[178:179]
	v_ldexp_f32 v170, v170, 1
	v_pk_mul_f32 v[174:175], v[174:175], v[180:181]
	v_ldexp_f32 v171, v171, 1
	v_pk_add_f32 v[178:179], v[172:173], v[174:175]
	v_pk_add_f32 v[176:177], v[182:183], v[184:185]
	v_pk_add_f32 v[172:173], v[178:179], v[172:173] neg_lo:[0,1] neg_hi:[0,1]
	v_pk_add_f32 v[182:183], v[176:177], v[182:183] neg_lo:[0,1] neg_hi:[0,1]
	v_pk_add_f32 v[172:173], v[174:175], v[172:173] neg_lo:[0,1] neg_hi:[0,1]
	v_pk_add_f32 v[182:183], v[184:185], v[182:183] neg_lo:[0,1] neg_hi:[0,1]
	v_pk_add_f32 v[170:171], v[170:171], v[172:173]
	v_add_f32_e32 v138, v139, v43
	v_pk_add_f32 v[190:191], v[178:179], v[170:171]
	v_mul_f32_e32 v138, 0xbfb8aa3b, v138
	v_pk_add_f32 v[172:173], v[190:191], v[178:179] neg_lo:[0,1] neg_hi:[0,1]
	v_exp_f32_e32 v138, v138
	v_pk_add_f32 v[170:171], v[170:171], v[172:173] neg_lo:[0,1] neg_hi:[0,1]
	v_add_f32_e32 v142, 1.0, v142
	v_pk_add_f32 v[184:185], v[182:183], v[170:171]
	v_add_f32_e32 v138, 1.0, v138
	v_pk_add_f32 v[172:173], v[184:185], v[182:183] neg_lo:[0,1] neg_hi:[0,1]
	v_rcp_f32_e32 v250, v138
	v_pk_add_f32 v[188:189], v[170:171], v[172:173] neg_lo:[0,1] neg_hi:[0,1]
	v_max_f32_e32 v170, v152, v152
	v_mul_f32_e64 v152, |v152|, s5
	v_exp_f32_e32 v236, v152
	v_pk_add_f32 v[174:175], v[184:185], v[172:173] neg_lo:[0,1] neg_hi:[0,1]
	v_min_f32_e32 v180, 0, v170
	v_pk_add_f32 v[186:187], v[182:183], v[174:175] neg_lo:[0,1] neg_hi:[0,1]
	v_add_f32_e32 v172, 1.0, v236
	v_add_f32_e32 v152, -1.0, v172
	v_sub_f32_e32 v170, v152, v172
	v_add_f32_e32 v170, 1.0, v170
	v_sub_f32_e32 v152, v236, v152
	v_add_f32_e32 v173, v152, v170
	v_max_f32_e32 v152, v153, v153
	v_min_f32_e32 v181, 0, v152
	v_mul_f32_e64 v152, |v153|, s5
	v_exp_f32_e32 v238, v152
	v_cvt_f64_f32_e32 v[170:171], v172
	v_frexp_exp_i32_f64_e32 v170, v[170:171]
	v_frexp_mant_f32_e32 v174, v172
	v_add_f32_e32 v171, 1.0, v238
	v_add_f32_e32 v152, -1.0, v171
	v_sub_f32_e32 v153, v152, v171
	v_add_f32_e32 v153, 1.0, v153
	v_sub_f32_e32 v152, v238, v152
	v_add_f32_e32 v175, v152, v153
	v_frexp_mant_f32_e32 v178, v171
	v_cvt_f64_f32_e32 v[152:153], v171
	v_cmp_gt_f32_e32 vcc, s72, v174
	v_frexp_exp_i32_f64_e32 v152, v[152:153]
	v_cmp_gt_f32_e64 s[14:15], s72, v178
	v_subbrev_co_u32_e32 v207, vcc, 0, v170, vcc
	s_nop 0
	v_subbrev_co_u32_e64 v206, s[14:15], 0, v152, s[14:15]
	v_sub_u32_e32 v153, 0, v207
	v_ldexp_f32 v152, v172, v153
	v_sub_u32_e32 v172, 0, v206
	v_ldexp_f32 v170, v173, v153
	v_ldexp_f32 v153, v171, v172
	v_ldexp_f32 v171, v175, v172
	v_pk_add_f32 v[172:173], v[152:153], 1.0 op_sel_hi:[1,0]
	v_pk_add_f32 v[192:193], v[152:153], -1.0 op_sel_hi:[1,0]
	v_pk_add_f32 v[174:175], v[172:173], -1.0 op_sel_hi:[1,0]
	v_pk_add_f32 v[194:195], v[192:193], 1.0 op_sel_hi:[1,0]
	v_pk_add_f32 v[174:175], v[152:153], v[174:175] neg_lo:[0,1] neg_hi:[0,1]
	v_pk_add_f32 v[152:153], v[152:153], v[194:195] neg_lo:[0,1] neg_hi:[0,1]
	v_pk_add_f32 v[174:175], v[170:171], v[174:175]
	v_pk_add_f32 v[152:153], v[170:171], v[152:153]
	v_pk_add_f32 v[178:179], v[172:173], v[174:175]
	v_pk_add_f32 v[170:171], v[192:193], v[152:153]
	v_rcp_f32_e32 v182, v178
	v_rcp_f32_e32 v183, v179
	v_pk_add_f32 v[172:173], v[178:179], v[172:173] neg_lo:[0,1] neg_hi:[0,1]
	v_pk_add_f32 v[192:193], v[170:171], v[192:193] neg_lo:[0,1] neg_hi:[0,1]
	v_pk_add_f32 v[172:173], v[174:175], v[172:173] neg_lo:[0,1] neg_hi:[0,1]
	v_pk_mul_f32 v[194:195], v[170:171], v[182:183]
	v_pk_add_f32 v[152:153], v[152:153], v[192:193] neg_lo:[0,1] neg_hi:[0,1]
	v_pk_mul_f32 v[174:175], v[178:179], v[194:195]
	v_add_f32_e32 v138, v144, v48
	v_pk_fma_f32 v[192:193], v[194:195], v[178:179], v[174:175] neg_lo:[0,0,1] neg_hi:[0,0,1]
	v_mul_f32_e32 v138, 0xbfb8aa3b, v138
	v_pk_fma_f32 v[192:193], v[194:195], v[172:173], v[192:193]
	v_exp_f32_e32 v138, v138
	v_pk_add_f32 v[196:197], v[174:175], v[192:193]
	v_rcp_f32_e32 v142, v142
	v_pk_add_f32 v[198:199], v[170:171], v[196:197] neg_lo:[0,1] neg_hi:[0,1]
	v_pk_add_f32 v[174:175], v[196:197], v[174:175] neg_lo:[0,1] neg_hi:[0,1]
	v_pk_add_f32 v[170:171], v[170:171], v[198:199] neg_lo:[0,1] neg_hi:[0,1]
	v_add_f32_e32 v138, 1.0, v138
	v_pk_add_f32 v[170:171], v[170:171], v[196:197] neg_lo:[0,1] neg_hi:[0,1]
	v_min_f32_e32 v168, 0, v168
	v_pk_add_f32 v[152:153], v[152:153], v[170:171]
	v_pk_add_f32 v[170:171], v[174:175], v[192:193] neg_lo:[0,1] neg_hi:[0,1]
	v_add_f32_e32 v130, v130, v26
	v_pk_add_f32 v[152:153], v[170:171], v[152:153]
	v_mul_f32_e32 v130, 0xbfb8aa3b, v130
	v_pk_add_f32 v[170:171], v[198:199], v[152:153]
	v_exp_f32_e32 v130, v130
	v_pk_mul_f32 v[174:175], v[182:183], v[170:171]
	v_pk_add_f32 v[198:199], v[198:199], v[170:171] neg_lo:[0,1] neg_hi:[0,1]
	v_pk_mul_f32 v[192:193], v[178:179], v[174:175]
	v_pk_add_f32 v[152:153], v[152:153], v[198:199]
	v_pk_fma_f32 v[178:179], v[174:175], v[178:179], v[192:193] neg_lo:[0,0,1] neg_hi:[0,0,1]
	v_pk_add_f32 v[204:205], v[194:195], v[174:175]
	v_pk_fma_f32 v[172:173], v[174:175], v[172:173], v[178:179]
	v_add_f32_e32 v130, 1.0, v130
	v_pk_add_f32 v[178:179], v[192:193], v[172:173]
	v_mul_f32_e32 v134, 0xbfb8aa3b, v134
	v_pk_add_f32 v[200:201], v[170:171], v[178:179] neg_lo:[0,1] neg_hi:[0,1]
	v_pk_add_f32 v[196:197], v[178:179], v[192:193] neg_lo:[0,1] neg_hi:[0,1]
	v_pk_add_f32 v[202:203], v[170:171], v[200:201] neg_lo:[0,1] neg_hi:[0,1]
	v_mov_b32_e32 v170, v179
	v_mov_b32_e32 v192, v193
	v_mov_b32_e32 v193, v201
	v_pk_add_f32 v[202:203], v[202:203], v[178:179] neg_lo:[0,1] neg_hi:[0,1]
	v_pk_add_f32 v[170:171], v[170:171], v[192:193] neg_lo:[0,1] neg_hi:[0,1]
	v_mov_b32_e32 v178, v173
	v_pk_add_f32 v[170:171], v[170:171], v[178:179] neg_lo:[0,1] neg_hi:[0,1]
	v_pk_add_f32 v[196:197], v[196:197], v[172:173] neg_lo:[0,1] neg_hi:[0,1]
	v_mov_b32_e32 v203, v171
	v_pk_add_f32 v[152:153], v[152:153], v[202:203]
	v_mov_b32_e32 v197, v170
	v_pk_add_f32 v[152:153], v[196:197], v[152:153]
	v_pk_add_f32 v[170:171], v[204:205], v[194:195] neg_lo:[0,1] neg_hi:[0,1]
	v_pk_add_f32 v[152:153], v[200:201], v[152:153]
	v_pk_add_f32 v[170:171], v[174:175], v[170:171] neg_lo:[0,1] neg_hi:[0,1]
	v_pk_mul_f32 v[152:153], v[182:183], v[152:153]
	v_cvt_f32_i32_e32 v183, v206
	v_pk_add_f32 v[152:153], v[170:171], v[152:153]
	v_cvt_f32_i32_e32 v182, v207
	v_pk_add_f32 v[170:171], v[204:205], v[152:153]
	v_exp_f32_e32 v134, v134
	v_pk_mul_f32 v[174:175], v[170:171], v[170:171]
	v_pk_add_f32 v[172:173], v[170:171], v[204:205] neg_lo:[0,1] neg_hi:[0,1]
	v_pk_fma_f32 v[178:179], v[174:175], s[28:29], v[150:151] op_sel_hi:[1,0,0]
	v_pk_add_f32 v[152:153], v[152:153], v[172:173] neg_lo:[0,1] neg_hi:[0,1]
	v_ldexp_f32 v172, v170, 1
	v_pk_fma_f32 v[178:179], v[174:175], v[178:179], s[30:31] op_sel_hi:[1,1,0]
	v_ldexp_f32 v173, v171, 1
	v_pk_mul_f32 v[170:171], v[170:171], v[174:175]
	v_pk_mul_f32 v[192:193], v[182:183], s[34:35] op_sel_hi:[1,0]
	v_pk_mul_f32 v[170:171], v[170:171], v[178:179]
	v_ldexp_f32 v152, v152, 1
	v_pk_add_f32 v[174:175], v[172:173], v[170:171]
	v_pk_fma_f32 v[194:195], v[182:183], s[34:35], v[192:193] op_sel_hi:[1,0,1] neg_lo:[0,0,1] neg_hi:[0,0,1]
	v_pk_add_f32 v[172:173], v[174:175], v[172:173] neg_lo:[0,1] neg_hi:[0,1]
	v_ldexp_f32 v153, v153, 1
	v_pk_add_f32 v[170:171], v[170:171], v[172:173] neg_lo:[0,1] neg_hi:[0,1]
	v_pk_fma_f32 v[182:183], v[182:183], s[36:37], v[194:195] op_sel_hi:[1,0,1]
	v_pk_add_f32 v[152:153], v[152:153], v[170:171]
	v_pk_add_f32 v[202:203], v[192:193], v[182:183]
	v_pk_add_f32 v[210:211], v[174:175], v[152:153]
	v_pk_add_f32 v[192:193], v[202:203], v[192:193] neg_lo:[0,1] neg_hi:[0,1]
	v_pk_add_f32 v[170:171], v[210:211], v[174:175] neg_lo:[0,1] neg_hi:[0,1]
	v_pk_add_f32 v[182:183], v[182:183], v[192:193] neg_lo:[0,1] neg_hi:[0,1]
	v_pk_add_f32 v[152:153], v[152:153], v[170:171] neg_lo:[0,1] neg_hi:[0,1]
	v_add_f32_e32 v134, 1.0, v134
	v_pk_add_f32 v[204:205], v[182:183], v[152:153]
	v_rcp_f32_e32 v134, v134
	v_pk_add_f32 v[170:171], v[204:205], v[182:183] neg_lo:[0,1] neg_hi:[0,1]
	v_add_f32_e32 v126, v126, v46
	v_pk_add_f32 v[208:209], v[152:153], v[170:171] neg_lo:[0,1] neg_hi:[0,1]
	v_max_f32_e32 v152, v146, v146
	v_mul_f32_e64 v146, |v146|, s5
	v_exp_f32_e32 v235, v146
	v_pk_add_f32 v[172:173], v[204:205], v[170:171] neg_lo:[0,1] neg_hi:[0,1]
	v_min_f32_e32 v178, 0, v152
	v_pk_add_f32 v[206:207], v[182:183], v[172:173] neg_lo:[0,1] neg_hi:[0,1]
	v_add_f32_e32 v170, 1.0, v235
	v_add_f32_e32 v146, -1.0, v170
	v_sub_f32_e32 v152, v146, v170
	v_add_f32_e32 v152, 1.0, v152
	v_sub_f32_e32 v146, v235, v146
	v_add_f32_e32 v171, v146, v152
	v_max_f32_e32 v146, v147, v147
	v_min_f32_e32 v179, 0, v146
	v_mul_f32_e64 v146, |v147|, s5
	v_exp_f32_e32 v237, v146
	v_cvt_f64_f32_e32 v[152:153], v170
	v_frexp_exp_i32_f64_e32 v152, v[152:153]
	v_frexp_mant_f32_e32 v172, v170
	v_add_f32_e32 v153, 1.0, v237
	v_add_f32_e32 v146, -1.0, v153
	v_sub_f32_e32 v147, v146, v153
	v_add_f32_e32 v147, 1.0, v147
	v_sub_f32_e32 v146, v237, v146
	v_add_f32_e32 v173, v146, v147
	v_frexp_mant_f32_e32 v174, v153
	v_cvt_f64_f32_e32 v[146:147], v153
	v_cmp_gt_f32_e32 vcc, s72, v172
	v_frexp_exp_i32_f64_e32 v146, v[146:147]
	v_cmp_gt_f32_e64 s[14:15], s72, v174
	v_subbrev_co_u32_e32 v217, vcc, 0, v152, vcc
	s_nop 0
	v_subbrev_co_u32_e64 v216, s[14:15], 0, v146, s[14:15]
	v_sub_u32_e32 v147, 0, v217
	v_ldexp_f32 v146, v170, v147
	v_sub_u32_e32 v170, 0, v216
	v_ldexp_f32 v152, v171, v147
	v_ldexp_f32 v147, v153, v170
	v_ldexp_f32 v153, v173, v170
	v_pk_add_f32 v[170:171], v[146:147], 1.0 op_sel_hi:[1,0]
	v_pk_add_f32 v[192:193], v[146:147], -1.0 op_sel_hi:[1,0]
	v_pk_add_f32 v[172:173], v[170:171], -1.0 op_sel_hi:[1,0]
	v_pk_add_f32 v[194:195], v[192:193], 1.0 op_sel_hi:[1,0]
	v_pk_add_f32 v[172:173], v[146:147], v[172:173] neg_lo:[0,1] neg_hi:[0,1]
	v_pk_add_f32 v[146:147], v[146:147], v[194:195] neg_lo:[0,1] neg_hi:[0,1]
	v_pk_add_f32 v[172:173], v[152:153], v[172:173]
	v_pk_add_f32 v[146:147], v[152:153], v[146:147]
	v_pk_add_f32 v[174:175], v[170:171], v[172:173]
	v_pk_add_f32 v[152:153], v[192:193], v[146:147]
	v_rcp_f32_e32 v182, v174
	v_rcp_f32_e32 v183, v175
	v_pk_add_f32 v[170:171], v[174:175], v[170:171] neg_lo:[0,1] neg_hi:[0,1]
	v_pk_add_f32 v[192:193], v[152:153], v[192:193] neg_lo:[0,1] neg_hi:[0,1]
	v_pk_add_f32 v[170:171], v[172:173], v[170:171] neg_lo:[0,1] neg_hi:[0,1]
	v_pk_mul_f32 v[194:195], v[152:153], v[182:183]
	v_pk_add_f32 v[146:147], v[146:147], v[192:193] neg_lo:[0,1] neg_hi:[0,1]
	v_pk_mul_f32 v[172:173], v[174:175], v[194:195]
	v_mul_f32_e32 v126, 0xbfb8aa3b, v126
	v_pk_fma_f32 v[192:193], v[194:195], v[174:175], v[172:173] neg_lo:[0,0,1] neg_hi:[0,0,1]
	v_exp_f32_e32 v126, v126
	v_pk_fma_f32 v[192:193], v[194:195], v[170:171], v[192:193]
	v_add_f32_e32 v122, v122, v42
	v_pk_add_f32 v[196:197], v[172:173], v[192:193]
	v_add_f32_e32 v126, 1.0, v126
	v_pk_add_f32 v[198:199], v[152:153], v[196:197] neg_lo:[0,1] neg_hi:[0,1]
	v_pk_add_f32 v[172:173], v[196:197], v[172:173] neg_lo:[0,1] neg_hi:[0,1]
	v_pk_add_f32 v[152:153], v[152:153], v[198:199] neg_lo:[0,1] neg_hi:[0,1]
	v_rcp_f32_e32 v126, v126
	v_pk_add_f32 v[152:153], v[152:153], v[196:197] neg_lo:[0,1] neg_hi:[0,1]
	v_mul_f32_e32 v122, 0xbfb8aa3b, v122
	v_pk_add_f32 v[146:147], v[146:147], v[152:153]
	v_pk_add_f32 v[152:153], v[172:173], v[192:193] neg_lo:[0,1] neg_hi:[0,1]
	v_exp_f32_e32 v122, v122
	v_pk_add_f32 v[146:147], v[152:153], v[146:147]
	v_add_f32_e32 v123, v123, v43
	v_pk_add_f32 v[152:153], v[198:199], v[146:147]
	v_add_f32_e32 v122, 1.0, v122
	v_pk_mul_f32 v[172:173], v[182:183], v[152:153]
	v_pk_add_f32 v[198:199], v[198:199], v[152:153] neg_lo:[0,1] neg_hi:[0,1]
	v_pk_mul_f32 v[192:193], v[174:175], v[172:173]
	v_pk_add_f32 v[146:147], v[146:147], v[198:199]
	v_pk_fma_f32 v[174:175], v[172:173], v[174:175], v[192:193] neg_lo:[0,0,1] neg_hi:[0,0,1]
	v_pk_add_f32 v[214:215], v[194:195], v[172:173]
	v_pk_fma_f32 v[170:171], v[172:173], v[170:171], v[174:175]
	v_rcp_f32_e32 v122, v122
	v_pk_add_f32 v[174:175], v[192:193], v[170:171]
	v_mul_f32_e32 v123, 0xbfb8aa3b, v123
	v_pk_add_f32 v[200:201], v[152:153], v[174:175] neg_lo:[0,1] neg_hi:[0,1]
	v_pk_add_f32 v[196:197], v[174:175], v[192:193] neg_lo:[0,1] neg_hi:[0,1]
	v_pk_add_f32 v[212:213], v[152:153], v[200:201] neg_lo:[0,1] neg_hi:[0,1]
	v_mov_b32_e32 v152, v175
	v_mov_b32_e32 v192, v193
	v_mov_b32_e32 v193, v201
	v_pk_add_f32 v[212:213], v[212:213], v[174:175] neg_lo:[0,1] neg_hi:[0,1]
	v_pk_add_f32 v[152:153], v[152:153], v[192:193] neg_lo:[0,1] neg_hi:[0,1]
	v_mov_b32_e32 v174, v171
	v_pk_add_f32 v[152:153], v[152:153], v[174:175] neg_lo:[0,1] neg_hi:[0,1]
	v_pk_add_f32 v[196:197], v[196:197], v[170:171] neg_lo:[0,1] neg_hi:[0,1]
	v_mov_b32_e32 v213, v153
	v_pk_add_f32 v[146:147], v[146:147], v[212:213]
	v_mov_b32_e32 v197, v152
	v_pk_add_f32 v[146:147], v[196:197], v[146:147]
	v_pk_add_f32 v[152:153], v[214:215], v[194:195] neg_lo:[0,1] neg_hi:[0,1]
	v_pk_add_f32 v[146:147], v[200:201], v[146:147]
	v_pk_add_f32 v[152:153], v[172:173], v[152:153] neg_lo:[0,1] neg_hi:[0,1]
	v_pk_mul_f32 v[146:147], v[182:183], v[146:147]
	v_cvt_f32_i32_e32 v183, v216
	v_pk_add_f32 v[146:147], v[152:153], v[146:147]
	v_cvt_f32_i32_e32 v182, v217
	v_pk_add_f32 v[152:153], v[214:215], v[146:147]
	v_exp_f32_e32 v123, v123
	v_pk_mul_f32 v[172:173], v[152:153], v[152:153]
	v_pk_add_f32 v[170:171], v[152:153], v[214:215] neg_lo:[0,1] neg_hi:[0,1]
	v_pk_fma_f32 v[174:175], v[172:173], s[28:29], v[150:151] op_sel_hi:[1,0,0]
	v_pk_add_f32 v[146:147], v[146:147], v[170:171] neg_lo:[0,1] neg_hi:[0,1]
	v_ldexp_f32 v170, v152, 1
	v_pk_fma_f32 v[174:175], v[172:173], v[174:175], s[30:31] op_sel_hi:[1,1,0]
	v_ldexp_f32 v171, v153, 1
	v_pk_mul_f32 v[152:153], v[152:153], v[172:173]
	v_pk_mul_f32 v[194:195], v[182:183], s[34:35] op_sel_hi:[1,0]
	v_pk_mul_f32 v[152:153], v[152:153], v[174:175]
	v_ldexp_f32 v146, v146, 1
	v_pk_add_f32 v[172:173], v[170:171], v[152:153]
	v_pk_fma_f32 v[192:193], v[182:183], s[34:35], v[194:195] op_sel_hi:[1,0,1] neg_lo:[0,0,1] neg_hi:[0,0,1]
	v_pk_add_f32 v[170:171], v[172:173], v[170:171] neg_lo:[0,1] neg_hi:[0,1]
	v_ldexp_f32 v147, v147, 1
	v_pk_add_f32 v[152:153], v[152:153], v[170:171] neg_lo:[0,1] neg_hi:[0,1]
	v_pk_fma_f32 v[182:183], v[182:183], s[36:37], v[192:193] op_sel_hi:[1,0,1]
	v_pk_add_f32 v[146:147], v[146:147], v[152:153]
	v_pk_add_f32 v[192:193], v[194:195], v[182:183]
	v_pk_add_f32 v[200:201], v[172:173], v[146:147]
	v_pk_add_f32 v[194:195], v[192:193], v[194:195] neg_lo:[0,1] neg_hi:[0,1]
	v_pk_add_f32 v[152:153], v[200:201], v[172:173] neg_lo:[0,1] neg_hi:[0,1]
	v_pk_add_f32 v[182:183], v[182:183], v[194:195] neg_lo:[0,1] neg_hi:[0,1]
	v_pk_add_f32 v[146:147], v[146:147], v[152:153] neg_lo:[0,1] neg_hi:[0,1]
	v_add_f32_e32 v123, 1.0, v123
	v_pk_add_f32 v[194:195], v[182:183], v[146:147]
	v_rcp_f32_e32 v123, v123
	v_pk_add_f32 v[152:153], v[194:195], v[182:183] neg_lo:[0,1] neg_hi:[0,1]
	v_add_f32_e32 v124, v124, v44
	v_pk_add_f32 v[170:171], v[194:195], v[152:153] neg_lo:[0,1] neg_hi:[0,1]
	v_pk_add_f32 v[198:199], v[146:147], v[152:153] neg_lo:[0,1] neg_hi:[0,1]
	v_max_f32_e32 v146, v148, v148
	v_pk_add_f32 v[196:197], v[182:183], v[170:171] neg_lo:[0,1] neg_hi:[0,1]
	v_min_f32_e32 v182, 0, v146
	v_mul_f32_e64 v146, |v148|, s5
	v_exp_f32_e32 v239, v146
	v_mul_f32_e32 v124, 0xbfb8aa3b, v124
	v_exp_f32_e32 v124, v124
	v_add_f32_e32 v118, v118, v30
	v_add_f32_e32 v148, 1.0, v239
	v_add_f32_e32 v146, -1.0, v148
	v_sub_f32_e32 v147, v146, v148
	v_add_f32_e32 v147, 1.0, v147
	v_sub_f32_e32 v146, v239, v146
	v_add_f32_e32 v152, v146, v147
	v_cvt_f64_f32_e32 v[146:147], v148
	v_frexp_exp_i32_f64_e32 v170, v[146:147]
	v_max_f32_e32 v146, v149, v149
	v_min_f32_e32 v183, 0, v146
	v_mul_f32_e64 v146, |v149|, s5
	v_exp_f32_e32 v240, v146
	v_frexp_mant_f32_e32 v153, v148
	v_cmp_gt_f32_e32 vcc, s72, v153
	v_add_f32_e32 v124, 1.0, v124
	v_add_f32_e32 v149, 1.0, v240
	v_add_f32_e32 v146, -1.0, v149
	v_sub_f32_e32 v147, v146, v149
	v_add_f32_e32 v147, 1.0, v147
	v_sub_f32_e32 v146, v240, v146
	v_add_f32_e32 v171, v146, v147
	v_frexp_mant_f32_e32 v172, v149
	v_cvt_f64_f32_e32 v[146:147], v149
	v_frexp_exp_i32_f64_e32 v146, v[146:147]
	v_cmp_gt_f32_e64 s[14:15], s72, v172
	v_subbrev_co_u32_e32 v241, vcc, 0, v170, vcc
	s_nop 0
	v_subbrev_co_u32_e64 v234, s[14:15], 0, v146, s[14:15]
	v_sub_u32_e32 v147, 0, v241
	v_ldexp_f32 v146, v148, v147
	v_ldexp_f32 v148, v152, v147
	v_sub_u32_e32 v152, 0, v234
	v_ldexp_f32 v147, v149, v152
	v_ldexp_f32 v149, v171, v152
	v_pk_add_f32 v[152:153], v[146:147], 1.0 op_sel_hi:[1,0]
	v_pk_add_f32 v[212:213], v[146:147], -1.0 op_sel_hi:[1,0]
	v_pk_add_f32 v[170:171], v[152:153], -1.0 op_sel_hi:[1,0]
	v_pk_add_f32 v[214:215], v[212:213], 1.0 op_sel_hi:[1,0]
	v_pk_add_f32 v[170:171], v[146:147], v[170:171] neg_lo:[0,1] neg_hi:[0,1]
	v_pk_add_f32 v[146:147], v[146:147], v[214:215] neg_lo:[0,1] neg_hi:[0,1]
	v_pk_add_f32 v[170:171], v[148:149], v[170:171]
	v_pk_add_f32 v[146:147], v[148:149], v[146:147]
	v_pk_add_f32 v[172:173], v[152:153], v[170:171]
	v_pk_add_f32 v[148:149], v[212:213], v[146:147]
	v_rcp_f32_e32 v174, v172
	v_rcp_f32_e32 v175, v173
	v_pk_add_f32 v[152:153], v[172:173], v[152:153] neg_lo:[0,1] neg_hi:[0,1]
	v_pk_add_f32 v[212:213], v[148:149], v[212:213] neg_lo:[0,1] neg_hi:[0,1]
	v_pk_add_f32 v[152:153], v[170:171], v[152:153] neg_lo:[0,1] neg_hi:[0,1]
	v_pk_mul_f32 v[214:215], v[148:149], v[174:175]
	v_pk_add_f32 v[146:147], v[146:147], v[212:213] neg_lo:[0,1] neg_hi:[0,1]
	v_pk_mul_f32 v[170:171], v[172:173], v[214:215]
	v_cmp_lt_f32_e64 s[14:15], |v233|, s77
	v_pk_fma_f32 v[212:213], v[214:215], v[172:173], v[170:171] neg_lo:[0,0,1] neg_hi:[0,0,1]
	v_rcp_f32_e32 v124, v124
	v_pk_fma_f32 v[212:213], v[214:215], v[152:153], v[212:213]
	v_add_f32_e32 v125, v125, v45
	v_pk_add_f32 v[216:217], v[170:171], v[212:213]
	v_mul_f32_e32 v118, 0xbfb8aa3b, v118
	v_pk_add_f32 v[218:219], v[148:149], v[216:217] neg_lo:[0,1] neg_hi:[0,1]
	v_pk_add_f32 v[170:171], v[216:217], v[170:171] neg_lo:[0,1] neg_hi:[0,1]
	v_pk_add_f32 v[148:149], v[148:149], v[218:219] neg_lo:[0,1] neg_hi:[0,1]
	v_mul_f32_e32 v125, 0xbfb8aa3b, v125
	v_pk_add_f32 v[148:149], v[148:149], v[216:217] neg_lo:[0,1] neg_hi:[0,1]
	v_exp_f32_e32 v118, v118
	v_pk_add_f32 v[146:147], v[146:147], v[148:149]
	v_pk_add_f32 v[148:149], v[170:171], v[212:213] neg_lo:[0,1] neg_hi:[0,1]
	v_exp_f32_e32 v125, v125
	v_pk_add_f32 v[146:147], v[148:149], v[146:147]
	v_add_f32_e32 v118, 1.0, v118
	v_pk_add_f32 v[148:149], v[218:219], v[146:147]
	v_add_f32_e32 v125, 1.0, v125
	v_pk_mul_f32 v[170:171], v[174:175], v[148:149]
	v_pk_add_f32 v[218:219], v[218:219], v[148:149] neg_lo:[0,1] neg_hi:[0,1]
	v_pk_mul_f32 v[212:213], v[172:173], v[170:171]
	v_pk_add_f32 v[146:147], v[146:147], v[218:219]
	v_pk_fma_f32 v[172:173], v[170:171], v[172:173], v[212:213] neg_lo:[0,0,1] neg_hi:[0,0,1]
	v_pk_add_f32 v[244:245], v[214:215], v[170:171]
	v_pk_fma_f32 v[152:153], v[170:171], v[152:153], v[172:173]
	v_rcp_f32_e32 v118, v118
	v_pk_add_f32 v[172:173], v[212:213], v[152:153]
	v_rcp_f32_e32 v125, v125
	v_pk_add_f32 v[220:221], v[148:149], v[172:173] neg_lo:[0,1] neg_hi:[0,1]
	v_pk_add_f32 v[216:217], v[172:173], v[212:213] neg_lo:[0,1] neg_hi:[0,1]
	v_pk_add_f32 v[242:243], v[148:149], v[220:221] neg_lo:[0,1] neg_hi:[0,1]
	v_mov_b32_e32 v148, v173
	v_mov_b32_e32 v212, v213
	v_mov_b32_e32 v213, v221
	v_pk_add_f32 v[242:243], v[242:243], v[172:173] neg_lo:[0,1] neg_hi:[0,1]
	v_pk_add_f32 v[148:149], v[148:149], v[212:213] neg_lo:[0,1] neg_hi:[0,1]
	v_mov_b32_e32 v172, v153
	v_pk_add_f32 v[148:149], v[148:149], v[172:173] neg_lo:[0,1] neg_hi:[0,1]
	v_pk_add_f32 v[216:217], v[216:217], v[152:153] neg_lo:[0,1] neg_hi:[0,1]
	v_mov_b32_e32 v243, v149
	v_pk_add_f32 v[146:147], v[146:147], v[242:243]
	v_mov_b32_e32 v217, v148
	v_pk_add_f32 v[146:147], v[216:217], v[146:147]
	v_pk_add_f32 v[148:149], v[244:245], v[214:215] neg_lo:[0,1] neg_hi:[0,1]
	v_pk_add_f32 v[146:147], v[220:221], v[146:147]
	v_pk_add_f32 v[148:149], v[170:171], v[148:149] neg_lo:[0,1] neg_hi:[0,1]
	v_pk_mul_f32 v[146:147], v[174:175], v[146:147]
	v_cvt_f32_i32_e32 v173, v234
	v_pk_add_f32 v[146:147], v[148:149], v[146:147]
	v_cvt_f32_i32_e32 v172, v241
	v_pk_add_f32 v[148:149], v[244:245], v[146:147]
	v_add_u32_e32 v234, s0, v167
	v_pk_mul_f32 v[170:171], v[148:149], v[148:149]
	v_pk_add_f32 v[152:153], v[148:149], v[244:245] neg_lo:[0,1] neg_hi:[0,1]
	v_pk_fma_f32 v[150:151], v[170:171], s[28:29], v[150:151] op_sel_hi:[1,0,0]
	v_pk_add_f32 v[146:147], v[146:147], v[152:153] neg_lo:[0,1] neg_hi:[0,1]
	v_ldexp_f32 v152, v148, 1
	v_pk_fma_f32 v[150:151], v[170:171], v[150:151], s[30:31] op_sel_hi:[1,1,0]
	v_ldexp_f32 v153, v149, 1
	v_pk_mul_f32 v[148:149], v[148:149], v[170:171]
	v_pk_mul_f32 v[174:175], v[172:173], s[34:35] op_sel_hi:[1,0]
	v_pk_mul_f32 v[148:149], v[148:149], v[150:151]
	v_ldexp_f32 v146, v146, 1
	v_pk_add_f32 v[150:151], v[152:153], v[148:149]
	v_pk_fma_f32 v[212:213], v[172:173], s[34:35], v[174:175] op_sel_hi:[1,0,1] neg_lo:[0,0,1] neg_hi:[0,0,1]
	v_pk_add_f32 v[152:153], v[150:151], v[152:153] neg_lo:[0,1] neg_hi:[0,1]
	v_ldexp_f32 v147, v147, 1
	v_pk_add_f32 v[148:149], v[148:149], v[152:153] neg_lo:[0,1] neg_hi:[0,1]
	v_pk_fma_f32 v[172:173], v[172:173], s[36:37], v[212:213] op_sel_hi:[1,0,1]
	v_pk_add_f32 v[146:147], v[146:147], v[148:149]
	v_pk_add_f32 v[212:213], v[174:175], v[172:173]
	v_pk_add_f32 v[220:221], v[150:151], v[146:147]
	v_pk_add_f32 v[174:175], v[212:213], v[174:175] neg_lo:[0,1] neg_hi:[0,1]
	v_pk_add_f32 v[148:149], v[220:221], v[150:151] neg_lo:[0,1] neg_hi:[0,1]
	v_pk_add_f32 v[172:173], v[172:173], v[174:175] neg_lo:[0,1] neg_hi:[0,1]
	v_pk_add_f32 v[146:147], v[146:147], v[148:149] neg_lo:[0,1] neg_hi:[0,1]
	v_ashrrev_i32_e32 v167, 31, v166
	v_pk_add_f32 v[214:215], v[172:173], v[146:147]
	v_mov_b32_e32 v242, v190
	v_pk_add_f32 v[148:149], v[214:215], v[172:173] neg_lo:[0,1] neg_hi:[0,1]
	v_mov_b32_e32 v243, v176
	v_pk_add_f32 v[218:219], v[146:147], v[148:149] neg_lo:[0,1] neg_hi:[0,1]
	v_mov_b32_e32 v146, v234
	v_pk_add_f32 v[150:151], v[214:215], v[148:149] neg_lo:[0,1] neg_hi:[0,1]
	v_ashrrev_i32_e32 v147, 31, v146
	v_lshlrev_b64 v[146:147], 10, v[146:147]
	v_lshl_add_u64 v[146:147], v[146:147], 0, v[166:167]
	v_lshlrev_b64 v[148:149], 1, v[146:147]
	v_lshl_add_u64 v[174:175], s[24:25], 0, v[148:149]
	v_pk_add_f32 v[216:217], v[172:173], v[150:151] neg_lo:[0,1] neg_hi:[0,1]
	global_load_dwordx4 v[150:153], v[174:175], off
	v_lshl_add_u64 v[170:171], s[50:51], 0, v[146:147]
	v_add_co_u32_e32 v146, vcc, s84, v174
	v_lshl_add_u64 v[172:173], s[48:49], 0, v[148:149]
	s_nop 0
	v_addc_co_u32_e32 v147, vcc, 0, v175, vcc
	global_load_dwordx4 v[146:149], v[146:147], off
	v_cmp_neq_f32_e32 vcc, s73, v232
	v_add_f32_e32 v114, v114, v26
	v_add_f32_e32 v119, v119, v31
	v_mul_f32_e32 v114, 0xbfb8aa3b, v114
	v_mul_f32_e32 v119, 0xbfb8aa3b, v119
	v_exp_f32_e32 v114, v114
	v_exp_f32_e32 v119, v119
	v_add_f32_e32 v120, v120, v32
	v_add_f32_e32 v115, v115, v27
	v_add_f32_e32 v114, 1.0, v114
	v_add_f32_e32 v119, 1.0, v119
	v_rcp_f32_e32 v114, v114
	v_rcp_f32_e32 v119, v119
	v_mul_f32_e32 v120, 0xbfb8aa3b, v120
	v_mul_f32_e32 v115, 0xbfb8aa3b, v115
	v_exp_f32_e32 v120, v120
	v_exp_f32_e32 v115, v115
	v_add_f32_e32 v121, v121, v33
	v_add_f32_e32 v116, v116, v28
	v_add_f32_e32 v120, 1.0, v120
	v_add_f32_e32 v115, 1.0, v115
	v_rcp_f32_e32 v120, v120
	v_rcp_f32_e32 v115, v115
	v_mul_f32_e32 v121, 0xbfb8aa3b, v121
	v_mul_f32_e32 v116, 0xbfb8aa3b, v116
	v_exp_f32_e32 v121, v121
	v_exp_f32_e32 v116, v116
	v_add_f32_e32 v117, v117, v29
	v_mul_f32_e32 v117, 0xbfb8aa3b, v117
	v_add_f32_e32 v121, 1.0, v121
	v_add_f32_e32 v116, 1.0, v116
	v_rcp_f32_e32 v121, v121
	v_rcp_f32_e32 v116, v116
	v_exp_f32_e32 v117, v117
	s_waitcnt vmcnt(0) lgkmcnt(0)
	v_lshlrev_b32_e32 v241, 16, v150
	v_and_b32_e32 v246, 0xffff0000, v150
	v_rcp_f32_e32 v150, v138
	v_add_f32_e32 v138, v140, v44
	v_mul_f32_e32 v138, 0xbfb8aa3b, v138
	v_exp_f32_e32 v138, v138
	v_lshlrev_b32_e32 v247, 16, v151
	v_and_b32_e32 v248, 0xffff0000, v151
	v_add_f32_e32 v117, 1.0, v117
	v_add_f32_e32 v138, 1.0, v138
	v_rcp_f32_e32 v251, v138
	v_add_f32_e32 v138, v145, v49
	v_mul_f32_e32 v138, 0xbfb8aa3b, v138
	v_exp_f32_e32 v138, v138
	v_rcp_f32_e32 v117, v117
	v_add_f32_e32 v138, 1.0, v138
	v_rcp_f32_e32 v151, v138
	v_add_f32_e32 v138, v141, v45
	v_mul_f32_e32 v138, 0xbfb8aa3b, v138
	v_exp_f32_e32 v138, v138
	s_nop 0
	v_add_f32_e32 v138, 1.0, v138
	v_rcp_f32_e32 v252, v138
	v_pk_add_f32 v[138:139], v[176:177], v[190:191]
	s_nop 0
	v_pk_add_f32 v[140:141], v[138:139], v[176:177] neg_lo:[0,1] neg_hi:[0,1]
	v_mov_b32_e32 v176, v191
	v_pk_add_f32 v[144:145], v[138:139], v[140:141] neg_lo:[0,1] neg_hi:[0,1]
	v_mov_b32_e32 v244, v140
	v_mov_b32_e32 v245, v144
	v_mov_b32_e32 v144, v141
	v_pk_add_f32 v[242:243], v[242:243], v[244:245] neg_lo:[0,1] neg_hi:[0,1]
	v_pk_add_f32 v[140:141], v[176:177], v[144:145] neg_lo:[0,1] neg_hi:[0,1]
	v_pk_add_f32 v[242:243], v[242:243], v[242:243] op_sel:[0,1] op_sel_hi:[1,0]
	v_pk_add_f32 v[140:141], v[140:141], v[140:141] op_sel_hi:[0,1]
	v_mov_b32_e32 v243, v185
	v_mov_b32_e32 v185, v141
	v_pk_add_f32 v[140:141], v[242:243], v[184:185]
	v_pk_add_f32 v[176:177], v[188:189], v[186:187]
	v_pk_add_f32 v[144:145], v[138:139], v[140:141]
	s_nop 0
	v_pk_add_f32 v[138:139], v[144:145], v[138:139] neg_lo:[0,1] neg_hi:[0,1]
	s_nop 0
	v_pk_add_f32 v[138:139], v[140:141], v[138:139] neg_lo:[0,1] neg_hi:[0,1]
	s_nop 0
	v_pk_add_f32 v[138:139], v[176:177], v[138:139]
	v_mov_b32_e32 v176, v210
	v_pk_add_f32 v[138:139], v[144:145], v[138:139]
	v_mov_b32_e32 v177, v202
	v_cndmask_b32_e32 v138, v228, v138, vcc
	v_cmp_neq_f32_e32 vcc, s73, v233
	s_nop 1
	v_cndmask_b32_e32 v139, v228, v139, vcc
	v_cmp_ngt_f32_e32 vcc, -1.0, v233
	s_nop 1
	v_cndmask_b32_e32 v139, v229, v139, vcc
	v_cmp_ngt_f32_e32 vcc, -1.0, v232
	s_nop 1
	v_cndmask_b32_e32 v138, v229, v138, vcc
	v_cmp_neq_f32_e32 vcc, -1.0, v232
	s_nop 1
	v_cndmask_b32_e32 v138, v230, v138, vcc
	v_cmp_neq_f32_e32 vcc, -1.0, v233
	s_nop 1
	v_cndmask_b32_e32 v139, v230, v139, vcc
	v_cmp_lt_f32_e64 vcc, |v232|, s77
	v_cndmask_b32_e64 v139, v139, v233, s[14:15]
	v_cmp_lt_f32_e64 s[14:15], |v238|, s77
	v_cndmask_b32_e32 v138, v138, v232, vcc
	v_pk_add_f32 v[138:139], v[168:169], v[138:139] neg_lo:[0,1] neg_hi:[0,1]
	v_cmp_neq_f32_e32 vcc, s73, v236
	v_pk_mul_f32 v[144:145], v[138:139], s[38:39] op_sel_hi:[1,0]
	s_nop 0
	v_pk_mul_f32 v[138:139], v[142:143], v[144:145]
	v_mul_f32_e32 v126, v126, v144
	v_add_f32_e32 v140, v138, v138
	v_mul_f32_e32 v140, 0x3fb8aa3b, v140
	v_exp_f32_e32 v140, v140
	v_cvt_pk_bf16_f32 v138, v138, v139
	v_sub_f32_e32 v140, 1.0, v140
	v_max_f32_e32 v140, 0, v140
	v_sqrt_f32_e32 v140, v140
	s_nop 0
	v_mul_f32_e32 v140, v249, v140
	v_mul_f32_e32 v186, v140, v241
	v_add_f32_e32 v140, v139, v139
	v_mul_f32_e32 v140, 0x3fb8aa3b, v140
	v_exp_f32_e32 v140, v140
	s_nop 0
	v_sub_f32_e32 v140, 1.0, v140
	v_max_f32_e32 v140, 0, v140
	v_sqrt_f32_e32 v140, v140
	s_nop 0
	v_mul_f32_e32 v140, v250, v140
	v_mul_f32_e32 v187, v140, v246
	v_pk_add_f32 v[140:141], v[202:203], v[210:211]
	s_nop 0
	v_pk_add_f32 v[142:143], v[140:141], v[202:203] neg_lo:[0,1] neg_hi:[0,1]
	v_mov_b32_e32 v202, v211
	v_pk_add_f32 v[168:169], v[140:141], v[142:143] neg_lo:[0,1] neg_hi:[0,1]
	v_mov_b32_e32 v184, v142
	v_mov_b32_e32 v185, v168
	v_mov_b32_e32 v168, v143
	v_pk_add_f32 v[176:177], v[176:177], v[184:185] neg_lo:[0,1] neg_hi:[0,1]
	v_pk_add_f32 v[142:143], v[202:203], v[168:169] neg_lo:[0,1] neg_hi:[0,1]
	v_pk_add_f32 v[176:177], v[176:177], v[176:177] op_sel:[0,1] op_sel_hi:[1,0]
	v_pk_add_f32 v[142:143], v[142:143], v[142:143] op_sel_hi:[0,1]
	v_mov_b32_e32 v177, v205
	v_mov_b32_e32 v205, v143
	v_pk_add_f32 v[142:143], v[176:177], v[204:205]
	v_pk_add_f32 v[176:177], v[208:209], v[206:207]
	v_pk_add_f32 v[168:169], v[140:141], v[142:143]
	s_nop 0
	v_pk_add_f32 v[140:141], v[168:169], v[140:141] neg_lo:[0,1] neg_hi:[0,1]
	s_nop 0
	v_pk_add_f32 v[140:141], v[142:143], v[140:141] neg_lo:[0,1] neg_hi:[0,1]
	s_nop 0
	v_pk_add_f32 v[140:141], v[176:177], v[140:141]
	v_rcp_f32_e32 v177, v130
	v_add_f32_e32 v130, v135, v31
	v_pk_add_f32 v[140:141], v[168:169], v[140:141]
	v_mul_f32_e32 v130, 0xbfb8aa3b, v130
	v_cndmask_b32_e32 v139, v228, v140, vcc
	v_cmp_neq_f32_e32 vcc, s73, v238
	v_exp_f32_e32 v130, v130
	v_and_b32_e32 v176, 0xffff0000, v152
	v_cndmask_b32_e32 v140, v228, v141, vcc
	v_cmp_ngt_f32_e32 vcc, -1.0, v238
	v_add_f32_e32 v130, 1.0, v130
	v_rcp_f32_e32 v135, v130
	v_cndmask_b32_e32 v140, v229, v140, vcc
	v_cmp_ngt_f32_e32 vcc, -1.0, v236
	v_add_f32_e32 v130, v131, v27
	v_mul_f32_e32 v130, 0xbfb8aa3b, v130
	v_cndmask_b32_e32 v139, v229, v139, vcc
	v_cmp_neq_f32_e32 vcc, -1.0, v236
	v_exp_f32_e32 v130, v130
	s_nop 0
	v_cndmask_b32_e32 v139, v230, v139, vcc
	v_cmp_neq_f32_e32 vcc, -1.0, v238
	v_add_f32_e32 v130, 1.0, v130
	v_rcp_f32_e32 v184, v130
	v_cndmask_b32_e32 v140, v230, v140, vcc
	v_cmp_lt_f32_e64 vcc, |v236|, s77
	v_cndmask_b32_e64 v141, v140, v238, s[14:15]
	v_add_f32_e32 v130, v136, v32
	v_cndmask_b32_e32 v140, v139, v236, vcc
	v_pk_add_f32 v[140:141], v[180:181], v[140:141] neg_lo:[0,1] neg_hi:[0,1]
	v_mul_f32_e32 v130, 0xbfb8aa3b, v130
	v_pk_mul_f32 v[142:143], v[140:141], s[38:39] op_sel_hi:[1,0]
	v_exp_f32_e32 v130, v130
	v_pk_mul_f32 v[140:141], v[150:151], v[142:143]
	v_lshlrev_b32_e32 v180, 16, v153
	v_add_f32_e32 v139, v140, v140
	v_mul_f32_e32 v139, 0x3fb8aa3b, v139
	v_exp_f32_e32 v139, v139
	v_add_f32_e32 v130, 1.0, v130
	v_rcp_f32_e32 v136, v130
	v_add_f32_e32 v130, v132, v28
	v_sub_f32_e32 v139, 1.0, v139
	v_max_f32_e32 v139, 0, v139
	v_sqrt_f32_e32 v139, v139
	v_mul_f32_e32 v130, 0xbfb8aa3b, v130
	v_exp_f32_e32 v130, v130
	v_and_b32_e32 v181, 0xffff0000, v153
	v_mul_f32_e32 v139, v251, v139
	v_mul_f32_e32 v150, v139, v247
	v_add_f32_e32 v139, v141, v141
	v_mul_f32_e32 v139, 0x3fb8aa3b, v139
	v_exp_f32_e32 v139, v139
	v_add_f32_e32 v130, 1.0, v130
	v_rcp_f32_e32 v185, v130
	v_add_f32_e32 v130, v137, v33
	v_mul_f32_e32 v130, 0xbfb8aa3b, v130
	v_exp_f32_e32 v130, v130
	v_sub_f32_e32 v139, 1.0, v139
	v_max_f32_e32 v139, 0, v139
	v_sqrt_f32_e32 v139, v139
	v_add_f32_e32 v130, 1.0, v130
	v_rcp_f32_e32 v137, v130
	v_add_f32_e32 v130, v133, v29
	v_mul_f32_e32 v130, 0xbfb8aa3b, v130
	v_mul_f32_e32 v139, v252, v139
	v_exp_f32_e32 v130, v130
	v_mul_f32_e32 v151, v139, v248
	v_cvt_pk_bf16_f32 v139, v140, v141
	v_mul_f32_e32 v140, 0x42000000, v186
	v_mul_f32_e32 v141, 0x42000000, v187
	v_mul_f32_e32 v168, 0x42000000, v150
	v_med3_f32 v140, v140, s29, v231
	v_med3_f32 v141, v141, s29, v231
	v_mov_b32_e32 v150, 0
	v_cvt_pk_fp8_f32 v150, v140, v141
	v_add_f32_e32 v130, 1.0, v130
	v_mul_f32_e32 v151, 0x42000000, v151
	v_rcp_f32_e32 v186, v130
	v_pk_add_f32 v[130:131], v[192:193], v[200:201]
	v_med3_f32 v140, v168, s29, v231
	v_med3_f32 v141, v151, s29, v231
	v_pk_add_f32 v[132:133], v[130:131], v[192:193] neg_lo:[0,1] neg_hi:[0,1]
	v_cvt_pk_fp8_f32 v150, v140, v141 op_sel:[0,0,1]
	v_pk_add_f32 v[140:141], v[130:131], v[132:133] neg_lo:[0,1] neg_hi:[0,1]
	v_lshlrev_b32_e32 v151, 16, v152
	v_mov_b32_e32 v152, v200
	v_mov_b32_e32 v153, v192
	v_mov_b32_e32 v168, v132
	v_mov_b32_e32 v169, v140
	v_mov_b32_e32 v192, v201
	v_mov_b32_e32 v140, v133
	v_pk_add_f32 v[152:153], v[152:153], v[168:169] neg_lo:[0,1] neg_hi:[0,1]
	v_pk_add_f32 v[132:133], v[192:193], v[140:141] neg_lo:[0,1] neg_hi:[0,1]
	v_pk_add_f32 v[152:153], v[152:153], v[152:153] op_sel:[0,1] op_sel_hi:[1,0]
	v_pk_add_f32 v[132:133], v[132:133], v[132:133] op_sel_hi:[0,1]
	v_mov_b32_e32 v153, v195
	v_mov_b32_e32 v195, v133
	v_pk_add_f32 v[132:133], v[152:153], v[194:195]
	v_pk_add_f32 v[152:153], v[198:199], v[196:197]
	v_pk_add_f32 v[140:141], v[130:131], v[132:133]
	v_cmp_neq_f32_e32 vcc, s73, v235
	v_pk_add_f32 v[130:131], v[140:141], v[130:131] neg_lo:[0,1] neg_hi:[0,1]
	v_cmp_lt_f32_e64 s[14:15], |v237|, s77
	v_pk_add_f32 v[130:131], v[132:133], v[130:131] neg_lo:[0,1] neg_hi:[0,1]
	v_mov_b32_e32 v168, v220
	v_pk_add_f32 v[130:131], v[152:153], v[130:131]
	v_mov_b32_e32 v169, v212
	v_pk_add_f32 v[130:131], v[140:141], v[130:131]
	s_nop 0
	v_cndmask_b32_e32 v130, v228, v130, vcc
	v_cmp_neq_f32_e32 vcc, s73, v237
	s_nop 1
	v_cndmask_b32_e32 v131, v228, v131, vcc
	v_cmp_ngt_f32_e32 vcc, -1.0, v237
	s_nop 1
	v_cndmask_b32_e32 v131, v229, v131, vcc
	v_cmp_ngt_f32_e32 vcc, -1.0, v235
	s_nop 1
	v_cndmask_b32_e32 v130, v229, v130, vcc
	v_cmp_neq_f32_e32 vcc, -1.0, v235
	s_nop 1
	v_cndmask_b32_e32 v130, v230, v130, vcc
	v_cmp_neq_f32_e32 vcc, -1.0, v237
	s_nop 1
	v_cndmask_b32_e32 v131, v230, v131, vcc
	v_cmp_lt_f32_e64 vcc, |v235|, s77
	v_cndmask_b32_e64 v131, v131, v237, s[14:15]
	v_cmp_lt_f32_e64 s[14:15], |v240|, s77
	v_cndmask_b32_e32 v130, v130, v235, vcc
	v_pk_add_f32 v[130:131], v[178:179], v[130:131] neg_lo:[0,1] neg_hi:[0,1]
	v_cmp_neq_f32_e32 vcc, s73, v239
	v_pk_mul_f32 v[130:131], v[130:131], s[38:39] op_sel_hi:[1,0]
	s_nop 0
	v_pk_mul_f32 v[132:133], v[134:135], v[130:131]
	v_mul_f32_e32 v118, v118, v130
	v_add_f32_e32 v134, v132, v132
	v_mul_f32_e32 v134, 0x3fb8aa3b, v134
	v_exp_f32_e32 v134, v134
	v_cvt_pk_bf16_f32 v140, v132, v133
	v_mul_f32_e32 v119, v119, v131
	v_sub_f32_e32 v134, 1.0, v134
	v_max_f32_e32 v134, 0, v134
	v_sqrt_f32_e32 v134, v134
	s_nop 0
	v_mul_f32_e32 v134, v177, v134
	v_mul_f32_e32 v151, v134, v151
	v_add_f32_e32 v134, v133, v133
	v_mul_f32_e32 v134, 0x3fb8aa3b, v134
	v_exp_f32_e32 v134, v134
	v_pk_add_f32 v[132:133], v[212:213], v[220:221]
	v_sub_f32_e32 v134, 1.0, v134
	v_max_f32_e32 v134, 0, v134
	v_sqrt_f32_e32 v134, v134
	s_nop 0
	v_mul_f32_e32 v134, v184, v134
	v_mul_f32_e32 v178, v134, v176
	v_pk_add_f32 v[134:135], v[132:133], v[212:213] neg_lo:[0,1] neg_hi:[0,1]
	v_mov_b32_e32 v212, v221
	v_pk_add_f32 v[152:153], v[132:133], v[134:135] neg_lo:[0,1] neg_hi:[0,1]
	v_mov_b32_e32 v176, v134
	v_mov_b32_e32 v177, v152
	v_mov_b32_e32 v152, v135
	v_pk_add_f32 v[168:169], v[168:169], v[176:177] neg_lo:[0,1] neg_hi:[0,1]
	v_pk_add_f32 v[134:135], v[212:213], v[152:153] neg_lo:[0,1] neg_hi:[0,1]
	v_pk_add_f32 v[168:169], v[168:169], v[168:169] op_sel:[0,1] op_sel_hi:[1,0]
	v_pk_add_f32 v[134:135], v[134:135], v[134:135] op_sel_hi:[0,1]
	v_mov_b32_e32 v169, v215
	v_mov_b32_e32 v215, v135
	v_pk_add_f32 v[134:135], v[168:169], v[214:215]
	v_pk_add_f32 v[168:169], v[218:219], v[216:217]
	v_pk_add_f32 v[152:153], v[132:133], v[134:135]
	s_nop 0
	v_pk_add_f32 v[132:133], v[152:153], v[132:133] neg_lo:[0,1] neg_hi:[0,1]
	s_nop 0
	v_pk_add_f32 v[132:133], v[134:135], v[132:133] neg_lo:[0,1] neg_hi:[0,1]
	s_nop 0
	v_pk_add_f32 v[132:133], v[168:169], v[132:133]
	s_nop 0
	v_pk_add_f32 v[132:133], v[152:153], v[132:133]
	s_nop 0
	v_cndmask_b32_e32 v132, v228, v132, vcc
	v_cmp_neq_f32_e32 vcc, s73, v240
	s_nop 1
	v_cndmask_b32_e32 v133, v228, v133, vcc
	v_cmp_ngt_f32_e32 vcc, -1.0, v240
	s_nop 1
	v_cndmask_b32_e32 v133, v229, v133, vcc
	v_cmp_ngt_f32_e32 vcc, -1.0, v239
	s_nop 1
	v_cndmask_b32_e32 v132, v229, v132, vcc
	v_cmp_neq_f32_e32 vcc, -1.0, v239
	s_nop 1
	v_cndmask_b32_e32 v132, v230, v132, vcc
	v_cmp_neq_f32_e32 vcc, -1.0, v240
	s_nop 1
	v_cndmask_b32_e32 v133, v230, v133, vcc
	v_cmp_lt_f32_e64 vcc, |v239|, s77
	v_cndmask_b32_e64 v133, v133, v240, s[14:15]
	s_nop 0
	v_cndmask_b32_e32 v132, v132, v239, vcc
	v_pk_add_f32 v[132:133], v[182:183], v[132:133] neg_lo:[0,1] neg_hi:[0,1]
	s_nop 0
	v_pk_mul_f32 v[132:133], v[132:133], s[38:39] op_sel_hi:[1,0]
	s_nop 0
	v_pk_mul_f32 v[134:135], v[136:137], v[132:133]
	v_mul_f32_e32 v120, v120, v132
	v_add_f32_e32 v136, v134, v134
	v_add_f32_e32 v137, v135, v135
	v_mul_f32_e32 v136, 0x3fb8aa3b, v136
	v_mul_f32_e32 v137, 0x3fb8aa3b, v137
	v_exp_f32_e32 v136, v136
	v_exp_f32_e32 v137, v137
	v_cvt_pk_bf16_f32 v141, v134, v135
	v_mul_f32_e32 v134, 0x42000000, v151
	v_sub_f32_e32 v136, 1.0, v136
	v_sub_f32_e32 v137, 1.0, v137
	v_max_f32_e32 v136, 0, v136
	v_max_f32_e32 v137, 0, v137
	v_sqrt_f32_e32 v136, v136
	v_sqrt_f32_e32 v137, v137
	v_mul_f32_e32 v135, 0x42000000, v178
	v_med3_f32 v134, v134, s29, v231
	v_med3_f32 v135, v135, s29, v231
	v_mov_b32_e32 v151, 0
	v_mul_f32_e32 v136, v185, v136
	v_mul_f32_e32 v137, v186, v137
	v_cvt_pk_fp8_f32 v151, v134, v135
	v_mul_f32_e32 v136, v136, v180
	v_mul_f32_e32 v137, v137, v181
	v_mul_f32_e32 v136, 0x42000000, v136
	v_mul_f32_e32 v137, 0x42000000, v137
	v_med3_f32 v134, v136, s29, v231
	v_med3_f32 v135, v137, s29, v231
	v_cvt_pk_fp8_f32 v151, v134, v135 op_sel:[0,0,1]
	global_store_dwordx4 v[172:173], v[138:141], off nt
	global_store_dwordx2 v[170:171], v[150:151], off nt
	s_nop 0
	v_add_f32_e32 v138, v126, v126
	v_mul_f32_e32 v138, 0x3fb8aa3b, v138
	v_exp_f32_e32 v138, v138
	v_lshlrev_b32_e32 v134, 16, v146
	v_and_b32_e32 v135, 0xffff0000, v146
	v_lshlrev_b32_e32 v136, 16, v147
	v_sub_f32_e32 v138, 1.0, v138
	v_max_f32_e32 v138, 0, v138
	v_sqrt_f32_e32 v138, v138
	v_and_b32_e32 v137, 0xffff0000, v147
	v_mul_f32_e32 v121, v121, v133
	v_mul_f32_e32 v122, v122, v138
	v_mul_f32_e32 v134, v122, v134
	v_add_f32_e32 v122, v127, v47
	v_mul_f32_e32 v122, 0xbfb8aa3b, v122
	v_exp_f32_e32 v122, v122
	s_nop 0
	v_add_f32_e32 v122, 1.0, v122
	v_rcp_f32_e32 v122, v122
	s_nop 0
	v_mul_f32_e32 v122, v122, v145
	v_add_f32_e32 v127, v122, v122
	v_mul_f32_e32 v127, 0x3fb8aa3b, v127
	v_exp_f32_e32 v127, v127
	v_cvt_pk_bf16_f32 v122, v126, v122
	v_mul_f32_e32 v126, 0x42000000, v134
	v_sub_f32_e32 v127, 1.0, v127
	v_max_f32_e32 v127, 0, v127
	v_sqrt_f32_e32 v127, v127
	s_nop 0
	v_mul_f32_e32 v123, v123, v127
	v_mul_f32_e32 v127, v123, v135
	v_add_f32_e32 v123, v128, v48
	v_mul_f32_e32 v123, 0xbfb8aa3b, v123
	v_exp_f32_e32 v123, v123
	v_mul_f32_e32 v127, 0x42000000, v127
	v_med3_f32 v127, v127, s29, v231
	v_add_f32_e32 v123, 1.0, v123
	v_rcp_f32_e32 v123, v123
	s_nop 0
	v_mul_f32_e32 v123, v123, v142
	v_add_f32_e32 v128, v123, v123
	v_mul_f32_e32 v128, 0x3fb8aa3b, v128
	v_exp_f32_e32 v128, v128
	s_nop 0
	v_sub_f32_e32 v128, 1.0, v128
	v_max_f32_e32 v128, 0, v128
	v_sqrt_f32_e32 v128, v128
	s_nop 0
	v_mul_f32_e32 v124, v124, v128
	v_add_f32_e32 v128, v129, v49
	v_mul_f32_e32 v128, 0xbfb8aa3b, v128
	v_exp_f32_e32 v128, v128
	v_mul_f32_e32 v124, v124, v136
	v_mul_f32_e32 v124, 0x42000000, v124
	v_med3_f32 v124, v124, s29, v231
	v_add_f32_e32 v128, 1.0, v128
	v_rcp_f32_e32 v128, v128
	s_nop 0
	v_mul_f32_e32 v128, v128, v143
	v_add_f32_e32 v129, v128, v128
	v_mul_f32_e32 v129, 0x3fb8aa3b, v129
	v_exp_f32_e32 v129, v129
	v_cvt_pk_bf16_f32 v123, v123, v128
	v_med3_f32 v128, v126, s29, v231
	v_mov_b32_e32 v126, 0
	v_sub_f32_e32 v129, 1.0, v129
	v_max_f32_e32 v129, 0, v129
	v_sqrt_f32_e32 v129, v129
	v_cvt_pk_fp8_f32 v126, v128, v127
	v_lshlrev_b32_e32 v127, 16, v149
	v_and_b32_e32 v128, 0xffff0000, v149
	v_mul_f32_e32 v125, v125, v129
	v_add_f32_e32 v129, v118, v118
	v_mul_f32_e32 v129, 0x3fb8aa3b, v129
	v_exp_f32_e32 v129, v129
	v_mul_f32_e32 v125, v125, v137
	v_mul_f32_e32 v125, 0x42000000, v125
	v_med3_f32 v125, v125, s29, v231
	v_sub_f32_e32 v129, 1.0, v129
	v_max_f32_e32 v129, 0, v129
	v_sqrt_f32_e32 v129, v129
	v_cvt_pk_fp8_f32 v126, v124, v125 op_sel:[0,0,1]
	v_lshlrev_b32_e32 v124, 16, v148
	v_and_b32_e32 v125, 0xffff0000, v148
	v_mul_f32_e32 v114, v114, v129
	v_mul_f32_e32 v114, v114, v124
	v_add_f32_e32 v124, v119, v119
	v_mul_f32_e32 v124, 0x3fb8aa3b, v124
	v_exp_f32_e32 v124, v124
	v_mul_f32_e32 v114, 0x42000000, v114
	v_med3_f32 v114, v114, s29, v231
	v_sub_f32_e32 v124, 1.0, v124
	v_max_f32_e32 v124, 0, v124
	v_sqrt_f32_e32 v124, v124
	s_nop 0
	v_mul_f32_e32 v115, v115, v124
	v_add_f32_e32 v124, v120, v120
	v_mul_f32_e32 v124, 0x3fb8aa3b, v124
	v_exp_f32_e32 v124, v124
	v_mul_f32_e32 v115, v115, v125
	v_mul_f32_e32 v115, 0x42000000, v115
	v_med3_f32 v115, v115, s29, v231
	v_sub_f32_e32 v124, 1.0, v124
	v_max_f32_e32 v124, 0, v124
	v_sqrt_f32_e32 v124, v124
	v_cvt_pk_bf16_f32 v125, v120, v121
	v_mul_f32_e32 v116, v116, v124
	v_add_f32_e32 v124, v121, v121
	v_mul_f32_e32 v124, 0x3fb8aa3b, v124
	v_exp_f32_e32 v124, v124
	v_mul_f32_e32 v116, v116, v127
	v_mov_b32_e32 v127, 0
	v_cvt_pk_fp8_f32 v127, v114, v115
	v_sub_f32_e32 v124, 1.0, v124
	v_max_f32_e32 v124, 0, v124
	v_sqrt_f32_e32 v124, v124
	v_mul_f32_e32 v116, 0x42000000, v116
	v_med3_f32 v114, v116, s29, v231
	v_mul_f32_e32 v117, v117, v124
	v_mul_f32_e32 v117, v117, v128
	v_mul_f32_e32 v117, 0x42000000, v117
	v_med3_f32 v115, v117, s29, v231
	v_cvt_pk_fp8_f32 v127, v114, v115 op_sel:[0,0,1]
	v_add_co_u32_e32 v114, vcc, s84, v172
	v_cvt_pk_bf16_f32 v124, v118, v119
	s_nop 0
	v_addc_co_u32_e32 v115, vcc, 0, v173, vcc
	global_store_dwordx4 v[114:115], v[122:125], off nt
	v_add_co_u32_e32 v114, vcc, s93, v170
	s_nop 1
	v_addc_co_u32_e32 v115, vcc, 0, v171, vcc
	global_store_dwordx2 v[114:115], v[126:127], off nt
	v_add_co_u32_e32 v114, vcc, s92, v174
	v_add_f32_e32 v110, v110, v46
	s_nop 0
	v_addc_co_u32_e32 v115, vcc, 0, v175, vcc
	global_load_dwordx4 v[114:117], v[114:115], off
	v_mul_f32_e32 v110, 0xbfb8aa3b, v110
	v_add_f32_e32 v111, v111, v47
	v_exp_f32_e32 v110, v110
	v_mul_f32_e32 v111, 0xbfb8aa3b, v111
	v_exp_f32_e32 v111, v111
	v_add_f32_e32 v112, v112, v48
	v_add_f32_e32 v113, v113, v49
	v_add_f32_e32 v110, 1.0, v110
	v_mul_f32_e32 v112, 0xbfb8aa3b, v112
	v_mul_f32_e32 v113, 0xbfb8aa3b, v113
	v_rcp_f32_e32 v110, v110
	v_exp_f32_e32 v112, v112
	v_exp_f32_e32 v113, v113
	v_add_f32_e32 v111, 1.0, v111
	v_rcp_f32_e32 v111, v111
	v_add_co_u32_e32 v118, vcc, s89, v174
	v_add_f32_e32 v120, v106, v42
	s_nop 0
	v_addc_co_u32_e32 v119, vcc, 0, v175, vcc
	v_add_f32_e32 v122, v108, v44
	v_mul_f32_e32 v110, v110, v144
	v_add_f32_e32 v121, v107, v43
	v_add_f32_e32 v123, v109, v45
	global_load_dwordx4 v[106:109], v[118:119], off
	v_mul_f32_e32 v118, 0xbfb8aa3b, v120
	v_mul_f32_e32 v120, 0xbfb8aa3b, v122
	v_add_f32_e32 v112, 1.0, v112
	v_add_f32_e32 v113, 1.0, v113
	v_add_f32_e32 v122, v110, v110
	v_rcp_f32_e32 v112, v112
	v_rcp_f32_e32 v113, v113
	v_mul_f32_e32 v111, v111, v145
	v_mul_f32_e32 v122, 0x3fb8aa3b, v122
	v_mul_f32_e32 v119, 0xbfb8aa3b, v121
	v_mul_f32_e32 v121, 0xbfb8aa3b, v123
	v_add_f32_e32 v123, v111, v111
	v_exp_f32_e32 v122, v122
	v_exp_f32_e32 v118, v118
	v_mul_f32_e32 v123, 0x3fb8aa3b, v123
	v_exp_f32_e32 v123, v123
	v_exp_f32_e32 v119, v119
	v_mul_f32_e32 v112, v112, v142
	v_mul_f32_e32 v113, v113, v143
	v_add_f32_e32 v124, v112, v112
	v_add_f32_e32 v125, v113, v113
	v_sub_f32_e32 v122, 1.0, v122
	v_add_f32_e32 v118, 1.0, v118
	v_mul_f32_e32 v124, 0x3fb8aa3b, v124
	v_mul_f32_e32 v125, 0x3fb8aa3b, v125
	v_max_f32_e32 v122, 0, v122
	v_rcp_f32_e32 v118, v118
	v_exp_f32_e32 v124, v124
	v_exp_f32_e32 v125, v125
	v_sub_f32_e32 v123, 1.0, v123
	v_sqrt_f32_e32 v122, v122
	v_exp_f32_e32 v120, v120
	v_exp_f32_e32 v121, v121
	v_add_f32_e32 v119, 1.0, v119
	v_max_f32_e32 v123, 0, v123
	v_rcp_f32_e32 v119, v119
	v_sqrt_f32_e32 v123, v123
	v_add_f32_e32 v102, v102, v30
	v_mul_f32_e32 v102, 0xbfb8aa3b, v102
	v_sub_f32_e32 v124, 1.0, v124
	v_sub_f32_e32 v125, 1.0, v125
	v_mul_f32_e32 v118, v118, v122
	v_exp_f32_e32 v102, v102
	v_add_f32_e32 v120, 1.0, v120
	v_add_f32_e32 v121, 1.0, v121
	v_max_f32_e32 v124, 0, v124
	v_rcp_f32_e32 v120, v120
	v_rcp_f32_e32 v121, v121
	v_sqrt_f32_e32 v124, v124
	v_mul_f32_e32 v119, v119, v123
	v_cvt_pk_bf16_f32 v110, v110, v111
	v_cvt_pk_bf16_f32 v111, v112, v113
	v_add_f32_e32 v102, 1.0, v102
	v_rcp_f32_e32 v102, v102
	s_waitcnt vmcnt(0) lgkmcnt(0)
	v_lshlrev_b32_e32 v122, 16, v114
	v_mul_f32_e32 v118, v118, v122
	v_max_f32_e32 v122, 0, v125
	v_and_b32_e32 v114, 0xffff0000, v114
	v_sqrt_f32_e32 v122, v122
	v_mul_f32_e32 v114, v119, v114
	v_mul_f32_e32 v112, 0x42000000, v118
	v_mul_f32_e32 v113, 0x42000000, v114
	v_med3_f32 v112, v112, s29, v231
	v_med3_f32 v113, v113, s29, v231
	v_mov_b32_e32 v114, 0
	v_lshlrev_b32_e32 v123, 16, v115
	v_and_b32_e32 v115, 0xffff0000, v115
	v_mul_f32_e32 v119, v120, v124
	v_mul_f32_e32 v120, v121, v122
	v_cvt_pk_fp8_f32 v114, v112, v113
	v_mul_f32_e32 v119, v119, v123
	v_mul_f32_e32 v115, v120, v115
	v_mul_f32_e32 v118, 0x42000000, v119
	v_mul_f32_e32 v112, 0x42000000, v115
	v_med3_f32 v113, v118, s29, v231
	v_med3_f32 v112, v112, s29, v231
	v_mul_f32_e32 v102, v102, v130
	v_cvt_pk_fp8_f32 v114, v113, v112 op_sel:[0,0,1]
	v_lshlrev_b32_e32 v112, 16, v116
	v_and_b32_e32 v113, 0xffff0000, v116
	v_add_f32_e32 v116, v102, v102
	v_add_f32_e32 v103, v103, v31
	v_add_f32_e32 v98, v98, v26
	v_mul_f32_e32 v116, 0x3fb8aa3b, v116
	v_mul_f32_e32 v103, 0xbfb8aa3b, v103
	v_mul_f32_e32 v98, 0xbfb8aa3b, v98
	v_exp_f32_e32 v116, v116
	v_exp_f32_e32 v103, v103
	v_exp_f32_e32 v98, v98
	v_add_f32_e32 v104, v104, v32
	v_sub_f32_e32 v116, 1.0, v116
	v_add_f32_e32 v103, 1.0, v103
	v_add_f32_e32 v98, 1.0, v98
	v_max_f32_e32 v116, 0, v116
	v_rcp_f32_e32 v103, v103
	v_rcp_f32_e32 v98, v98
	v_sqrt_f32_e32 v116, v116
	v_add_f32_e32 v105, v105, v33
	v_mul_f32_e32 v103, v103, v131
	v_add_f32_e32 v99, v99, v27
	v_mul_f32_e32 v98, v98, v116
	v_add_f32_e32 v116, v103, v103
	v_mul_f32_e32 v116, 0x3fb8aa3b, v116
	v_mul_f32_e32 v104, 0xbfb8aa3b, v104
	v_mul_f32_e32 v105, 0xbfb8aa3b, v105
	v_mul_f32_e32 v99, 0xbfb8aa3b, v99
	v_exp_f32_e32 v116, v116
	v_exp_f32_e32 v104, v104
	v_exp_f32_e32 v105, v105
	v_exp_f32_e32 v99, v99
	v_sub_f32_e32 v116, 1.0, v116
	v_add_f32_e32 v104, 1.0, v104
	v_add_f32_e32 v105, 1.0, v105
	v_add_f32_e32 v99, 1.0, v99
	v_max_f32_e32 v116, 0, v116
	v_rcp_f32_e32 v104, v104
	v_rcp_f32_e32 v105, v105
	v_rcp_f32_e32 v99, v99
	v_sqrt_f32_e32 v116, v116
	v_mul_f32_e32 v104, v104, v132
	v_mul_f32_e32 v105, v105, v133
	v_mul_f32_e32 v98, v98, v112
	v_mul_f32_e32 v99, v99, v116
	v_add_f32_e32 v112, v104, v104
	v_add_f32_e32 v116, v105, v105
	v_add_f32_e32 v100, v100, v28
	v_mul_f32_e32 v112, 0x3fb8aa3b, v112
	v_add_f32_e32 v101, v101, v29
	v_mul_f32_e32 v116, 0x3fb8aa3b, v116
	v_mul_f32_e32 v100, 0xbfb8aa3b, v100
	v_exp_f32_e32 v112, v112
	v_mul_f32_e32 v101, 0xbfb8aa3b, v101
	v_exp_f32_e32 v116, v116
	v_add_f32_e32 v94, v94, v46
	v_exp_f32_e32 v100, v100
	v_exp_f32_e32 v101, v101
	v_mul_f32_e32 v94, 0xbfb8aa3b, v94
	v_exp_f32_e32 v94, v94
	v_sub_f32_e32 v112, 1.0, v112
	v_sub_f32_e32 v116, 1.0, v116
	v_add_f32_e32 v100, 1.0, v100
	v_max_f32_e32 v112, 0, v112
	v_add_f32_e32 v101, 1.0, v101
	v_max_f32_e32 v116, 0, v116
	v_rcp_f32_e32 v100, v100
	v_sqrt_f32_e32 v112, v112
	v_rcp_f32_e32 v101, v101
	v_sqrt_f32_e32 v116, v116
	v_add_f32_e32 v94, 1.0, v94
	v_rcp_f32_e32 v94, v94
	v_mul_f32_e32 v99, v99, v113
	v_lshlrev_b32_e32 v115, 16, v117
	v_and_b32_e32 v117, 0xffff0000, v117
	v_mul_f32_e32 v100, v100, v112
	v_mul_f32_e32 v101, v101, v116
	v_mul_f32_e32 v98, 0x42000000, v98
	v_mul_f32_e32 v99, 0x42000000, v99
	v_mul_f32_e32 v100, v100, v115
	v_mul_f32_e32 v101, v101, v117
	v_med3_f32 v98, v98, s29, v231
	v_med3_f32 v99, v99, s29, v231
	v_mov_b32_e32 v115, 0
	v_mul_f32_e32 v94, v94, v144
	v_cvt_pk_fp8_f32 v115, v98, v99
	v_mul_f32_e32 v98, 0x42000000, v101
	v_add_f32_e32 v101, v94, v94
	v_add_f32_e32 v95, v95, v47
	v_add_f32_e32 v90, v90, v42
	v_mul_f32_e32 v101, 0x3fb8aa3b, v101
	v_mul_f32_e32 v95, 0xbfb8aa3b, v95
	v_mul_f32_e32 v90, 0xbfb8aa3b, v90
	v_exp_f32_e32 v101, v101
	v_exp_f32_e32 v95, v95
	v_exp_f32_e32 v90, v90
	v_add_f32_e32 v91, v91, v43
	v_sub_f32_e32 v101, 1.0, v101
	v_add_f32_e32 v95, 1.0, v95
	v_add_f32_e32 v90, 1.0, v90
	v_max_f32_e32 v101, 0, v101
	v_rcp_f32_e32 v95, v95
	v_rcp_f32_e32 v90, v90
	v_sqrt_f32_e32 v101, v101
	v_add_f32_e32 v96, v96, v48
	v_mul_f32_e32 v95, v95, v145
	v_mul_f32_e32 v91, 0xbfb8aa3b, v91
	v_mul_f32_e32 v90, v90, v101
	v_add_f32_e32 v101, v95, v95
	v_mul_f32_e32 v101, 0x3fb8aa3b, v101
	v_exp_f32_e32 v101, v101
	v_mul_f32_e32 v96, 0xbfb8aa3b, v96
	v_add_f32_e32 v97, v97, v49
	v_exp_f32_e32 v91, v91
	v_exp_f32_e32 v96, v96
	v_mul_f32_e32 v97, 0xbfb8aa3b, v97
	v_exp_f32_e32 v97, v97
	v_mul_f32_e32 v100, 0x42000000, v100
	v_med3_f32 v99, v100, s29, v231
	v_med3_f32 v98, v98, s29, v231
	v_sub_f32_e32 v101, 1.0, v101
	v_add_f32_e32 v92, v92, v44
	v_cvt_pk_fp8_f32 v115, v99, v98 op_sel:[0,0,1]
	v_add_co_u32_e32 v98, vcc, s92, v172
	v_add_f32_e32 v91, 1.0, v91
	v_max_f32_e32 v101, 0, v101
	v_add_f32_e32 v96, 1.0, v96
	v_mul_f32_e32 v92, 0xbfb8aa3b, v92
	v_cvt_pk_bf16_f32 v112, v102, v103
	v_cvt_pk_bf16_f32 v113, v104, v105
	v_addc_co_u32_e32 v99, vcc, 0, v173, vcc
	v_rcp_f32_e32 v91, v91
	v_sqrt_f32_e32 v101, v101
	v_exp_f32_e32 v92, v92
	v_rcp_f32_e32 v96, v96
	v_add_f32_e32 v97, 1.0, v97
	global_store_dwordx4 v[98:99], v[110:113], off nt
	v_add_co_u32_e32 v98, vcc, s84, v170
	v_rcp_f32_e32 v97, v97
	s_nop 0
	v_addc_co_u32_e32 v99, vcc, 0, v171, vcc
	global_store_dwordx2 v[98:99], v[114:115], off nt
	v_lshlrev_b32_e32 v98, 16, v106
	v_mul_f32_e32 v98, v90, v98
	v_mul_f32_e32 v90, v91, v101
	v_add_f32_e32 v91, 1.0, v92
	v_mul_f32_e32 v92, v96, v142
	v_add_f32_e32 v96, v92, v92
	v_mul_f32_e32 v97, v97, v143
	v_mul_f32_e32 v96, 0x3fb8aa3b, v96
	v_add_f32_e32 v101, v97, v97
	v_exp_f32_e32 v96, v96
	v_add_f32_e32 v93, v93, v45
	v_mul_f32_e32 v101, 0x3fb8aa3b, v101
	v_mul_f32_e32 v93, 0xbfb8aa3b, v93
	v_exp_f32_e32 v101, v101
	v_exp_f32_e32 v93, v93
	v_add_f32_e32 v86, v86, v30
	v_mul_f32_e32 v86, 0xbfb8aa3b, v86
	v_sub_f32_e32 v96, 1.0, v96
	v_exp_f32_e32 v86, v86
	v_max_f32_e32 v96, 0, v96
	v_sub_f32_e32 v101, 1.0, v101
	v_rcp_f32_e32 v91, v91
	v_sqrt_f32_e32 v96, v96
	v_add_f32_e32 v93, 1.0, v93
	v_max_f32_e32 v101, 0, v101
	v_rcp_f32_e32 v93, v93
	v_sqrt_f32_e32 v101, v101
	v_add_f32_e32 v86, 1.0, v86
	v_and_b32_e32 v99, 0xffff0000, v106
	v_rcp_f32_e32 v86, v86
	v_lshlrev_b32_e32 v100, 16, v107
	v_mul_f32_e32 v99, v90, v99
	v_mul_f32_e32 v90, v91, v96
	v_and_b32_e32 v102, 0xffff0000, v107
	v_mul_f32_e32 v96, v90, v100
	v_mul_f32_e32 v90, v93, v101
	v_mul_f32_e32 v93, v90, v102
	v_cvt_pk_bf16_f32 v90, v94, v95
	v_cvt_pk_bf16_f32 v91, v92, v97
	v_mul_f32_e32 v92, 0x42000000, v98
	v_mul_f32_e32 v94, 0x42000000, v99
	v_mul_f32_e32 v95, 0x42000000, v96
	v_med3_f32 v92, v92, s29, v231
	v_med3_f32 v96, v94, s29, v231
	v_mov_b32_e32 v94, 0
	v_mul_f32_e32 v86, v86, v130
	v_cvt_pk_fp8_f32 v94, v92, v96
	v_add_f32_e32 v96, v86, v86
	v_add_f32_e32 v87, v87, v31
	v_add_f32_e32 v82, v82, v26
	v_mul_f32_e32 v96, 0x3fb8aa3b, v96
	v_mul_f32_e32 v87, 0xbfb8aa3b, v87
	v_mul_f32_e32 v82, 0xbfb8aa3b, v82
	v_exp_f32_e32 v96, v96
	v_exp_f32_e32 v87, v87
	v_exp_f32_e32 v82, v82
	v_add_f32_e32 v88, v88, v32
	v_sub_f32_e32 v96, 1.0, v96
	v_add_f32_e32 v87, 1.0, v87
	v_add_f32_e32 v82, 1.0, v82
	v_max_f32_e32 v96, 0, v96
	v_rcp_f32_e32 v87, v87
	v_rcp_f32_e32 v82, v82
	v_sqrt_f32_e32 v96, v96
	v_mul_f32_e32 v88, 0xbfb8aa3b, v88
	v_mul_f32_e32 v87, v87, v131
	v_exp_f32_e32 v88, v88
	v_mul_f32_e32 v82, v82, v96
	v_add_f32_e32 v96, v87, v87
	v_add_f32_e32 v89, v89, v33
	v_add_f32_e32 v83, v83, v27
	v_mul_f32_e32 v96, 0x3fb8aa3b, v96
	v_mul_f32_e32 v89, 0xbfb8aa3b, v89
	v_mul_f32_e32 v83, 0xbfb8aa3b, v83
	v_exp_f32_e32 v96, v96
	v_exp_f32_e32 v89, v89
	v_exp_f32_e32 v83, v83
	v_add_f32_e32 v88, 1.0, v88
	v_rcp_f32_e32 v88, v88
	v_sub_f32_e32 v96, 1.0, v96
	v_add_f32_e32 v89, 1.0, v89
	v_mul_f32_e32 v92, 0x42000000, v93
	v_add_f32_e32 v83, 1.0, v83
	v_max_f32_e32 v96, 0, v96
	v_rcp_f32_e32 v89, v89
	v_med3_f32 v93, v95, s29, v231
	v_med3_f32 v92, v92, s29, v231
	v_rcp_f32_e32 v83, v83
	v_sqrt_f32_e32 v96, v96
	v_cvt_pk_fp8_f32 v94, v93, v92 op_sel:[0,0,1]
	v_lshlrev_b32_e32 v92, 16, v108
	v_mul_f32_e32 v88, v88, v132
	v_mul_f32_e32 v82, v82, v92
	v_add_f32_e32 v92, v88, v88
	v_add_f32_e32 v84, v84, v28
	v_mul_f32_e32 v92, 0x3fb8aa3b, v92
	v_mul_f32_e32 v89, v89, v133
	v_mul_f32_e32 v84, 0xbfb8aa3b, v84
	v_mul_f32_e32 v83, v83, v96
	v_exp_f32_e32 v92, v92
	v_add_f32_e32 v96, v89, v89
	v_exp_f32_e32 v84, v84
	v_add_f32_e32 v85, v85, v29
	v_mul_f32_e32 v96, 0x3fb8aa3b, v96
	v_mul_f32_e32 v85, 0xbfb8aa3b, v85
	v_exp_f32_e32 v96, v96
	v_exp_f32_e32 v85, v85
	v_sub_f32_e32 v92, 1.0, v92
	v_add_f32_e32 v84, 1.0, v84
	v_max_f32_e32 v92, 0, v92
	v_rcp_f32_e32 v84, v84
	v_sqrt_f32_e32 v92, v92
	v_sub_f32_e32 v96, 1.0, v96
	v_add_f32_e32 v85, 1.0, v85
	v_max_f32_e32 v96, 0, v96
	v_and_b32_e32 v93, 0xffff0000, v108
	v_rcp_f32_e32 v85, v85
	v_sqrt_f32_e32 v96, v96
	v_mul_f32_e32 v83, v83, v93
	v_lshlrev_b32_e32 v95, 16, v109
	v_mul_f32_e32 v84, v84, v92
	v_mul_f32_e32 v82, 0x42000000, v82
	v_mul_f32_e32 v83, 0x42000000, v83
	v_mul_f32_e32 v84, v84, v95
	v_med3_f32 v82, v82, s29, v231
	v_med3_f32 v83, v83, s29, v231
	v_mov_b32_e32 v95, 0
	v_and_b32_e32 v97, 0xffff0000, v109
	v_mul_f32_e32 v85, v85, v96
	v_cvt_pk_fp8_f32 v95, v82, v83
	v_mul_f32_e32 v85, v85, v97
	v_mul_f32_e32 v84, 0x42000000, v84
	v_mul_f32_e32 v82, 0x42000000, v85
	v_med3_f32 v83, v84, s29, v231
	v_med3_f32 v82, v82, s29, v231
	v_cvt_pk_fp8_f32 v95, v83, v82 op_sel:[0,0,1]
	v_add_co_u32_e32 v82, vcc, s89, v172
	v_cvt_pk_bf16_f32 v92, v86, v87
	v_cvt_pk_bf16_f32 v93, v88, v89
	v_addc_co_u32_e32 v83, vcc, 0, v173, vcc
	s_mov_b32 s0, 0xc000
	global_store_dwordx4 v[82:83], v[90:93], off nt
	v_add_co_u32_e32 v82, vcc, s0, v170
	s_nop 1
	v_addc_co_u32_e32 v83, vcc, 0, v171, vcc
	global_store_dwordx2 v[82:83], v[94:95], off nt
	v_add_u32_e32 v82, 0x80, v234
	v_add_f32_e32 v78, v78, v46
	v_ashrrev_i32_e32 v83, 31, v82
	v_lshlrev_b64 v[82:83], 10, v[82:83]
	v_lshl_add_u64 v[88:89], v[82:83], 0, v[166:167]
	v_lshlrev_b64 v[90:91], 1, v[88:89]
	v_lshl_add_u64 v[82:83], s[24:25], 0, v[90:91]
	global_load_dwordx4 v[84:87], v[82:83], off
	v_mul_f32_e32 v78, 0xbfb8aa3b, v78
	v_exp_f32_e32 v92, v78
	v_add_f32_e32 v79, v79, v47
	v_add_f32_e32 v80, v80, v48
	v_mul_f32_e32 v79, 0xbfb8aa3b, v79
	v_add_f32_e32 v74, v74, v42
	v_add_f32_e32 v81, v81, v49
	v_mul_f32_e32 v80, 0xbfb8aa3b, v80
	v_exp_f32_e32 v93, v79
	v_add_f32_e32 v75, v75, v43
	v_add_f32_e32 v76, v76, v44
	v_add_f32_e32 v77, v77, v45
	v_mul_f32_e32 v74, 0xbfb8aa3b, v74
	v_mul_f32_e32 v81, 0xbfb8aa3b, v81
	v_exp_f32_e32 v94, v80
	v_lshl_add_u64 v[78:79], s[50:51], 0, v[88:89]
	v_add_f32_e32 v88, 1.0, v92
	v_mul_f32_e32 v75, 0xbfb8aa3b, v75
	v_mul_f32_e32 v76, 0xbfb8aa3b, v76
	v_mul_f32_e32 v77, 0xbfb8aa3b, v77
	v_exp_f32_e32 v74, v74
	v_exp_f32_e32 v95, v81
	v_rcp_f32_e32 v88, v88
	v_exp_f32_e32 v75, v75
	v_exp_f32_e32 v76, v76
	v_exp_f32_e32 v77, v77
	v_lshl_add_u64 v[80:81], s[48:49], 0, v[90:91]
	v_add_f32_e32 v90, 1.0, v93
	v_add_f32_e32 v92, 1.0, v94
	v_rcp_f32_e32 v90, v90
	v_add_f32_e32 v89, 1.0, v74
	v_add_f32_e32 v93, 1.0, v95
	v_add_co_u32_e32 v74, vcc, s84, v82
	v_rcp_f32_e32 v92, v92
	v_mul_f32_e32 v88, v88, v144
	v_add_f32_e32 v91, 1.0, v75
	v_add_f32_e32 v76, 1.0, v76
	v_add_f32_e32 v77, 1.0, v77
	v_addc_co_u32_e32 v75, vcc, 0, v83, vcc
	v_rcp_f32_e32 v93, v93
	v_add_f32_e32 v96, v88, v88
	v_rcp_f32_e32 v94, v76
	v_rcp_f32_e32 v95, v77
	global_load_dwordx4 v[74:77], v[74:75], off
	v_mul_f32_e32 v96, 0x3fb8aa3b, v96
	v_mul_f32_e32 v90, v90, v145
	v_exp_f32_e32 v96, v96
	v_mul_f32_e32 v92, v92, v142
	v_add_f32_e32 v97, v90, v90
	v_mul_f32_e32 v93, v93, v143
	v_add_f32_e32 v98, v92, v92
	v_mul_f32_e32 v97, 0x3fb8aa3b, v97
	v_add_f32_e32 v99, v93, v93
	v_mul_f32_e32 v98, 0x3fb8aa3b, v98
	v_exp_f32_e32 v97, v97
	v_mul_f32_e32 v99, 0x3fb8aa3b, v99
	v_exp_f32_e32 v98, v98
	v_sub_f32_e32 v96, 1.0, v96
	v_exp_f32_e32 v99, v99
	v_max_f32_e32 v96, 0, v96
	v_rcp_f32_e32 v89, v89
	v_sqrt_f32_e32 v96, v96
	v_add_f32_e32 v70, v70, v30
	v_sub_f32_e32 v97, 1.0, v97
	v_mul_f32_e32 v70, 0xbfb8aa3b, v70
	v_sub_f32_e32 v98, 1.0, v98
	v_max_f32_e32 v97, 0, v97
	v_exp_f32_e32 v70, v70
	v_rcp_f32_e32 v91, v91
	v_sub_f32_e32 v99, 1.0, v99
	v_max_f32_e32 v98, 0, v98
	v_sqrt_f32_e32 v97, v97
	v_max_f32_e32 v99, 0, v99
	v_sqrt_f32_e32 v98, v98
	v_mul_f32_e32 v89, v89, v96
	v_add_f32_e32 v70, 1.0, v70
	v_mul_f32_e32 v91, v91, v97
	s_waitcnt vmcnt(0) lgkmcnt(0)
	v_lshlrev_b32_e32 v96, 16, v84
	v_mul_f32_e32 v89, v89, v96
	v_sqrt_f32_e32 v96, v99
	v_and_b32_e32 v84, 0xffff0000, v84
	v_rcp_f32_e32 v70, v70
	v_lshlrev_b32_e32 v97, 16, v85
	v_mul_f32_e32 v91, v91, v84
	v_mul_f32_e32 v84, v94, v98
	v_and_b32_e32 v85, 0xffff0000, v85
	v_mul_f32_e32 v94, v84, v97
	v_mul_f32_e32 v84, v95, v96
	v_mul_f32_e32 v95, v84, v85
	v_cvt_pk_bf16_f32 v84, v88, v90
	v_mul_f32_e32 v88, 0x42000000, v89
	v_mul_f32_e32 v89, 0x42000000, v91
	v_med3_f32 v91, v88, s29, v231
	v_med3_f32 v89, v89, s29, v231
	v_mov_b32_e32 v88, 0
	v_mul_f32_e32 v70, v70, v130
	v_cvt_pk_fp8_f32 v88, v91, v89
	v_add_f32_e32 v91, v70, v70
	v_add_f32_e32 v71, v71, v31
	v_add_f32_e32 v66, v66, v26
	v_mul_f32_e32 v91, 0x3fb8aa3b, v91
	v_mul_f32_e32 v71, 0xbfb8aa3b, v71
	v_mul_f32_e32 v66, 0xbfb8aa3b, v66
	v_exp_f32_e32 v91, v91
	v_exp_f32_e32 v71, v71
	v_exp_f32_e32 v66, v66
	v_add_f32_e32 v73, v73, v33
	v_sub_f32_e32 v91, 1.0, v91
	v_add_f32_e32 v71, 1.0, v71
	v_add_f32_e32 v66, 1.0, v66
	v_max_f32_e32 v91, 0, v91
	v_rcp_f32_e32 v71, v71
	v_rcp_f32_e32 v66, v66
	v_sqrt_f32_e32 v91, v91
	v_add_f32_e32 v67, v67, v27
	v_mul_f32_e32 v71, v71, v131
	v_add_f32_e32 v72, v72, v32
	v_mul_f32_e32 v66, v66, v91
	v_add_f32_e32 v91, v71, v71
	v_mul_f32_e32 v91, 0x3fb8aa3b, v91
	v_mul_f32_e32 v73, 0xbfb8aa3b, v73
	v_mul_f32_e32 v67, 0xbfb8aa3b, v67
	v_exp_f32_e32 v91, v91
	v_mul_f32_e32 v72, 0xbfb8aa3b, v72
	v_exp_f32_e32 v73, v73
	v_exp_f32_e32 v67, v67
	v_exp_f32_e32 v72, v72
	v_sub_f32_e32 v91, 1.0, v91
	v_add_f32_e32 v73, 1.0, v73
	v_add_f32_e32 v67, 1.0, v67
	v_max_f32_e32 v91, 0, v91
	v_add_f32_e32 v72, 1.0, v72
	v_rcp_f32_e32 v73, v73
	v_rcp_f32_e32 v67, v67
	v_sqrt_f32_e32 v91, v91
	v_rcp_f32_e32 v72, v72
	v_mul_f32_e32 v90, 0x42000000, v94
	v_mul_f32_e32 v89, 0x42000000, v95
	v_med3_f32 v90, v90, s29, v231
	v_med3_f32 v89, v89, s29, v231
	v_mul_f32_e32 v73, v73, v133
	v_cvt_pk_fp8_f32 v88, v90, v89 op_sel:[0,0,1]
	v_lshlrev_b32_e32 v89, 16, v86
	v_mul_f32_e32 v67, v67, v91
	v_mul_f32_e32 v72, v72, v132
	v_add_f32_e32 v91, v73, v73
	v_mul_f32_e32 v66, v66, v89
	v_add_f32_e32 v89, v72, v72
	v_add_f32_e32 v69, v69, v29
	v_mul_f32_e32 v91, 0x3fb8aa3b, v91
	v_add_f32_e32 v68, v68, v28
	v_mul_f32_e32 v89, 0x3fb8aa3b, v89
	v_mul_f32_e32 v69, 0xbfb8aa3b, v69
	v_exp_f32_e32 v91, v91
	v_add_f32_e32 v62, v62, v46
	v_mul_f32_e32 v68, 0xbfb8aa3b, v68
	v_exp_f32_e32 v89, v89
	v_exp_f32_e32 v69, v69
	v_mul_f32_e32 v62, 0xbfb8aa3b, v62
	v_exp_f32_e32 v68, v68
	v_exp_f32_e32 v62, v62
	v_sub_f32_e32 v91, 1.0, v91
	v_sub_f32_e32 v89, 1.0, v89
	v_add_f32_e32 v69, 1.0, v69
	v_max_f32_e32 v91, 0, v91
	v_add_f32_e32 v68, 1.0, v68
	v_max_f32_e32 v89, 0, v89
	v_rcp_f32_e32 v69, v69
	v_sqrt_f32_e32 v91, v91
	v_add_f32_e32 v62, 1.0, v62
	v_rcp_f32_e32 v68, v68
	v_sqrt_f32_e32 v89, v89
	v_rcp_f32_e32 v62, v62
	v_and_b32_e32 v86, 0xffff0000, v86
	v_mul_f32_e32 v67, v67, v86
	v_lshlrev_b32_e32 v90, 16, v87
	v_and_b32_e32 v87, 0xffff0000, v87
	v_mul_f32_e32 v69, v69, v91
	v_mul_f32_e32 v66, 0x42000000, v66
	v_mul_f32_e32 v67, 0x42000000, v67
	v_mul_f32_e32 v68, v68, v89
	v_mul_f32_e32 v69, v69, v87
	v_med3_f32 v66, v66, s29, v231
	v_med3_f32 v67, v67, s29, v231
	v_mov_b32_e32 v89, 0
	v_mul_f32_e32 v62, v62, v144
	v_cvt_pk_fp8_f32 v89, v66, v67
	v_mul_f32_e32 v66, 0x42000000, v69
	v_add_f32_e32 v69, v62, v62
	v_add_f32_e32 v63, v63, v47
	v_add_f32_e32 v58, v58, v42
	v_mul_f32_e32 v69, 0x3fb8aa3b, v69
	v_mul_f32_e32 v63, 0xbfb8aa3b, v63
	v_mul_f32_e32 v58, 0xbfb8aa3b, v58
	v_exp_f32_e32 v69, v69
	v_exp_f32_e32 v63, v63
	v_exp_f32_e32 v58, v58
	v_add_f32_e32 v59, v59, v43
	v_sub_f32_e32 v69, 1.0, v69
	v_add_f32_e32 v63, 1.0, v63
	v_add_f32_e32 v58, 1.0, v58
	v_max_f32_e32 v69, 0, v69
	v_rcp_f32_e32 v63, v63
	v_rcp_f32_e32 v58, v58
	v_sqrt_f32_e32 v69, v69
	v_add_f32_e32 v64, v64, v48
	v_mul_f32_e32 v63, v63, v145
	v_mul_f32_e32 v59, 0xbfb8aa3b, v59
	v_mul_f32_e32 v58, v58, v69
	v_add_f32_e32 v69, v63, v63
	v_mul_f32_e32 v69, 0x3fb8aa3b, v69
	v_exp_f32_e32 v69, v69
	v_mul_f32_e32 v64, 0xbfb8aa3b, v64
	v_add_f32_e32 v65, v65, v49
	v_exp_f32_e32 v59, v59
	v_exp_f32_e32 v64, v64
	v_mul_f32_e32 v65, 0xbfb8aa3b, v65
	v_exp_f32_e32 v65, v65
	v_sub_f32_e32 v69, 1.0, v69
	v_add_f32_e32 v60, v60, v44
	v_add_f32_e32 v59, 1.0, v59
	v_max_f32_e32 v69, 0, v69
	v_add_f32_e32 v64, 1.0, v64
	v_mul_f32_e32 v60, 0xbfb8aa3b, v60
	v_mul_f32_e32 v68, v68, v90
	v_rcp_f32_e32 v59, v59
	v_sqrt_f32_e32 v69, v69
	v_exp_f32_e32 v60, v60
	v_rcp_f32_e32 v64, v64
	v_add_f32_e32 v65, 1.0, v65
	v_mul_f32_e32 v68, 0x42000000, v68
	v_rcp_f32_e32 v65, v65
	v_med3_f32 v67, v68, s29, v231
	v_med3_f32 v66, v66, s29, v231
	v_cvt_pk_fp8_f32 v89, v67, v66 op_sel:[0,0,1]
	v_lshlrev_b32_e32 v66, 16, v74
	v_mul_f32_e32 v66, v58, v66
	v_mul_f32_e32 v58, v59, v69
	v_add_f32_e32 v59, 1.0, v60
	v_mul_f32_e32 v60, v64, v142
	v_add_f32_e32 v64, v60, v60
	v_mul_f32_e32 v65, v65, v143
	v_mul_f32_e32 v64, 0x3fb8aa3b, v64
	v_add_f32_e32 v69, v65, v65
	v_exp_f32_e32 v64, v64
	v_add_f32_e32 v61, v61, v45
	v_mul_f32_e32 v69, 0x3fb8aa3b, v69
	v_mul_f32_e32 v61, 0xbfb8aa3b, v61
	v_exp_f32_e32 v69, v69
	v_exp_f32_e32 v61, v61
	v_add_f32_e32 v54, v54, v30
	v_mul_f32_e32 v54, 0xbfb8aa3b, v54
	v_sub_f32_e32 v64, 1.0, v64
	v_exp_f32_e32 v54, v54
	v_max_f32_e32 v64, 0, v64
	v_sub_f32_e32 v69, 1.0, v69
	v_rcp_f32_e32 v59, v59
	v_sqrt_f32_e32 v64, v64
	v_add_f32_e32 v61, 1.0, v61
	v_max_f32_e32 v69, 0, v69
	v_rcp_f32_e32 v61, v61
	v_sqrt_f32_e32 v69, v69
	v_add_f32_e32 v54, 1.0, v54
	v_and_b32_e32 v67, 0xffff0000, v74
	v_rcp_f32_e32 v54, v54
	v_lshlrev_b32_e32 v68, 16, v75
	v_mul_f32_e32 v67, v58, v67
	v_mul_f32_e32 v58, v59, v64
	v_cvt_pk_bf16_f32 v86, v70, v71
	v_and_b32_e32 v70, 0xffff0000, v75
	v_mul_f32_e32 v64, v58, v68
	v_mul_f32_e32 v58, v61, v69
	v_mul_f32_e32 v61, v58, v70
	v_cvt_pk_bf16_f32 v58, v62, v63
	v_cvt_pk_bf16_f32 v59, v60, v65
	v_mul_f32_e32 v60, 0x42000000, v66
	v_mul_f32_e32 v62, 0x42000000, v67
	v_mul_f32_e32 v63, 0x42000000, v64
	v_med3_f32 v60, v60, s29, v231
	v_med3_f32 v64, v62, s29, v231
	v_mov_b32_e32 v62, 0
	v_mul_f32_e32 v54, v54, v130
	v_cvt_pk_fp8_f32 v62, v60, v64
	v_add_f32_e32 v64, v54, v54
	v_add_f32_e32 v55, v55, v31
	v_add_f32_e32 v50, v50, v26
	v_mul_f32_e32 v64, 0x3fb8aa3b, v64
	v_mul_f32_e32 v55, 0xbfb8aa3b, v55
	v_mul_f32_e32 v50, 0xbfb8aa3b, v50
	v_exp_f32_e32 v64, v64
	v_exp_f32_e32 v55, v55
	v_exp_f32_e32 v50, v50
	v_add_f32_e32 v56, v56, v32
	v_sub_f32_e32 v64, 1.0, v64
	v_add_f32_e32 v55, 1.0, v55
	v_add_f32_e32 v50, 1.0, v50
	v_max_f32_e32 v64, 0, v64
	v_rcp_f32_e32 v55, v55
	v_rcp_f32_e32 v50, v50
	v_sqrt_f32_e32 v64, v64
	v_mul_f32_e32 v56, 0xbfb8aa3b, v56
	v_mul_f32_e32 v55, v55, v131
	v_exp_f32_e32 v56, v56
	v_mul_f32_e32 v50, v50, v64
	v_add_f32_e32 v64, v55, v55
	v_add_f32_e32 v57, v57, v33
	v_add_f32_e32 v51, v51, v27
	v_mul_f32_e32 v64, 0x3fb8aa3b, v64
	v_mul_f32_e32 v57, 0xbfb8aa3b, v57
	v_mul_f32_e32 v51, 0xbfb8aa3b, v51
	v_exp_f32_e32 v64, v64
	v_exp_f32_e32 v57, v57
	v_exp_f32_e32 v51, v51
	v_add_f32_e32 v56, 1.0, v56
	v_rcp_f32_e32 v56, v56
	v_sub_f32_e32 v64, 1.0, v64
	v_add_f32_e32 v57, 1.0, v57
	v_mul_f32_e32 v60, 0x42000000, v61
	v_add_f32_e32 v51, 1.0, v51
	v_max_f32_e32 v64, 0, v64
	v_rcp_f32_e32 v57, v57
	v_med3_f32 v61, v63, s29, v231
	v_med3_f32 v60, v60, s29, v231
	v_rcp_f32_e32 v51, v51
	v_sqrt_f32_e32 v64, v64
	v_cvt_pk_fp8_f32 v62, v61, v60 op_sel:[0,0,1]
	v_lshlrev_b32_e32 v60, 16, v76
	v_mul_f32_e32 v56, v56, v132
	v_mul_f32_e32 v50, v50, v60
	v_add_f32_e32 v60, v56, v56
	v_add_f32_e32 v52, v52, v28
	v_mul_f32_e32 v60, 0x3fb8aa3b, v60
	v_mul_f32_e32 v57, v57, v133
	v_mul_f32_e32 v52, 0xbfb8aa3b, v52
	v_mul_f32_e32 v51, v51, v64
	v_exp_f32_e32 v60, v60
	v_add_f32_e32 v64, v57, v57
	v_exp_f32_e32 v52, v52
	v_add_f32_e32 v53, v53, v29
	v_mul_f32_e32 v64, 0x3fb8aa3b, v64
	v_mul_f32_e32 v53, 0xbfb8aa3b, v53
	v_exp_f32_e32 v64, v64
	v_exp_f32_e32 v53, v53
	v_sub_f32_e32 v60, 1.0, v60
	v_add_f32_e32 v52, 1.0, v52
	v_max_f32_e32 v60, 0, v60
	v_rcp_f32_e32 v52, v52
	v_sqrt_f32_e32 v60, v60
	v_sub_f32_e32 v64, 1.0, v64
	v_add_f32_e32 v53, 1.0, v53
	v_max_f32_e32 v64, 0, v64
	v_and_b32_e32 v61, 0xffff0000, v76
	v_rcp_f32_e32 v53, v53
	v_sqrt_f32_e32 v64, v64
	v_mul_f32_e32 v51, v51, v61
	v_lshlrev_b32_e32 v63, 16, v77
	v_mul_f32_e32 v52, v52, v60
	v_mul_f32_e32 v50, 0x42000000, v50
	v_mul_f32_e32 v51, 0x42000000, v51
	v_mul_f32_e32 v52, v52, v63
	v_med3_f32 v50, v50, s29, v231
	v_med3_f32 v51, v51, s29, v231
	v_mov_b32_e32 v63, 0
	v_and_b32_e32 v65, 0xffff0000, v77
	v_mul_f32_e32 v53, v53, v64
	v_cvt_pk_fp8_f32 v63, v50, v51
	v_mul_f32_e32 v53, v53, v65
	v_mul_f32_e32 v52, 0x42000000, v52
	v_mul_f32_e32 v50, 0x42000000, v53
	v_med3_f32 v51, v52, s29, v231
	v_med3_f32 v50, v50, s29, v231
	v_cvt_pk_fp8_f32 v63, v51, v50 op_sel:[0,0,1]
	v_add_co_u32_e32 v50, vcc, s84, v80
	v_cvt_pk_bf16_f32 v85, v92, v93
	v_cvt_pk_bf16_f32 v87, v72, v73
	v_cvt_pk_bf16_f32 v60, v54, v55
	v_cvt_pk_bf16_f32 v61, v56, v57
	v_addc_co_u32_e32 v51, vcc, 0, v81, vcc
	global_store_dwordx4 v[80:81], v[84:87], off nt
	global_store_dwordx2 v[78:79], v[88:89], off nt
	global_store_dwordx4 v[50:51], v[58:61], off nt
	v_add_co_u32_e32 v50, vcc, s93, v78
	s_nop 1
	v_addc_co_u32_e32 v51, vcc, 0, v79, vcc
	global_store_dwordx2 v[50:51], v[62:63], off nt
	v_add_co_u32_e32 v50, vcc, s92, v82
	v_add_f32_e32 v38, v38, v46
	s_nop 0
	v_addc_co_u32_e32 v51, vcc, 0, v83, vcc
	global_load_dwordx4 v[54:57], v[50:51], off
	v_mul_f32_e32 v38, 0xbfb8aa3b, v38
	v_exp_f32_e32 v38, v38
	v_add_f32_e32 v34, v34, v42
	v_mul_f32_e32 v34, 0xbfb8aa3b, v34
	v_exp_f32_e32 v34, v34
	v_add_f32_e32 v38, 1.0, v38
	v_rcp_f32_e32 v38, v38
	v_add_f32_e32 v39, v39, v47
	v_add_f32_e32 v34, 1.0, v34
	v_mul_f32_e32 v39, 0xbfb8aa3b, v39
	v_exp_f32_e32 v39, v39
	v_add_f32_e32 v35, v35, v43
	v_mul_f32_e32 v35, 0xbfb8aa3b, v35
	v_exp_f32_e32 v35, v35
	v_add_f32_e32 v39, 1.0, v39
	v_rcp_f32_e32 v39, v39
	v_add_f32_e32 v36, v36, v44
	v_add_f32_e32 v35, 1.0, v35
	v_rcp_f32_e32 v35, v35
	v_mul_f32_e32 v39, v39, v145
	v_mul_f32_e32 v36, 0xbfb8aa3b, v36
	v_exp_f32_e32 v36, v36
	v_add_co_u32_e32 v50, vcc, s89, v82
	v_add_f32_e32 v22, v22, v30
	v_add_f32_e32 v36, 1.0, v36
	v_rcp_f32_e32 v36, v36
	v_addc_co_u32_e32 v51, vcc, 0, v83, vcc
	global_load_dwordx4 v[50:53], v[50:51], off
	v_add_f32_e32 v37, v37, v45
	v_mul_f32_e32 v22, 0xbfb8aa3b, v22
	v_mul_f32_e32 v37, 0xbfb8aa3b, v37
	v_exp_f32_e32 v22, v22
	v_exp_f32_e32 v37, v37
	v_add_f32_e32 v18, v18, v26
	v_add_f32_e32 v23, v23, v31
	v_add_f32_e32 v22, 1.0, v22
	v_add_f32_e32 v37, 1.0, v37
	v_rcp_f32_e32 v22, v22
	v_rcp_f32_e32 v37, v37
	v_mul_f32_e32 v18, 0xbfb8aa3b, v18
	v_mul_f32_e32 v23, 0xbfb8aa3b, v23
	v_mul_f32_e32 v22, v22, v130
	v_exp_f32_e32 v18, v18
	v_exp_f32_e32 v23, v23
	v_add_f32_e32 v24, v24, v32
	v_add_f32_e32 v19, v19, v27
	v_add_f32_e32 v18, 1.0, v18
	v_add_f32_e32 v23, 1.0, v23
	v_rcp_f32_e32 v18, v18
	v_rcp_f32_e32 v23, v23
	v_mul_f32_e32 v24, 0xbfb8aa3b, v24
	v_mul_f32_e32 v19, 0xbfb8aa3b, v19
	v_exp_f32_e32 v24, v24
	v_mul_f32_e32 v23, v23, v131
	v_exp_f32_e32 v19, v19
	v_add_f32_e32 v25, v25, v33
	v_add_f32_e32 v24, 1.0, v24
	v_rcp_f32_e32 v24, v24
	v_add_f32_e32 v19, 1.0, v19
	v_rcp_f32_e32 v19, v19
	v_add_f32_e32 v20, v20, v28
	v_mul_f32_e32 v24, v24, v132
	v_mul_f32_e32 v25, 0xbfb8aa3b, v25
	v_mul_f32_e32 v20, 0xbfb8aa3b, v20
	v_exp_f32_e32 v25, v25
	v_exp_f32_e32 v20, v20
	v_add_f32_e32 v14, v14, v46
	v_add_f32_e32 v21, v21, v29
	v_add_f32_e32 v25, 1.0, v25
	v_add_f32_e32 v20, 1.0, v20
	v_rcp_f32_e32 v25, v25
	v_rcp_f32_e32 v20, v20
	v_mul_f32_e32 v14, 0xbfb8aa3b, v14
	v_mul_f32_e32 v21, 0xbfb8aa3b, v21
	v_mul_f32_e32 v25, v25, v133
	v_exp_f32_e32 v14, v14
	v_exp_f32_e32 v21, v21
	s_waitcnt vmcnt(0) lgkmcnt(0)
	v_lshlrev_b32_e32 v58, 16, v54
	v_and_b32_e32 v59, 0xffff0000, v54
	v_lshlrev_b32_e32 v60, 16, v55
	v_and_b32_e32 v54, 0xffff0000, v55
	v_rcp_f32_e32 v55, v34
	v_mul_f32_e32 v34, v38, v144
	v_add_f32_e32 v38, v34, v34
	v_mul_f32_e32 v38, 0x3fb8aa3b, v38
	v_exp_f32_e32 v38, v38
	v_cvt_pk_bf16_f32 v34, v34, v39
	v_add_f32_e32 v14, 1.0, v14
	v_add_f32_e32 v21, 1.0, v21
	v_sub_f32_e32 v38, 1.0, v38
	v_max_f32_e32 v38, 0, v38
	v_sqrt_f32_e32 v38, v38
	v_rcp_f32_e32 v14, v14
	v_rcp_f32_e32 v21, v21
	v_add_f32_e32 v10, v10, v42
	v_mul_f32_e32 v38, v55, v38
	v_add_f32_e32 v55, v39, v39
	v_mul_f32_e32 v55, 0x3fb8aa3b, v55
	v_exp_f32_e32 v55, v55
	v_mul_f32_e32 v38, v38, v58
	v_mul_f32_e32 v38, 0x42000000, v38
	v_mul_f32_e32 v14, v14, v144
	v_sub_f32_e32 v55, 1.0, v55
	v_max_f32_e32 v55, 0, v55
	v_sqrt_f32_e32 v55, v55
	v_mul_f32_e32 v10, 0xbfb8aa3b, v10
	v_exp_f32_e32 v10, v10
	v_add_f32_e32 v11, v11, v43
	v_mul_f32_e32 v35, v35, v55
	v_mul_f32_e32 v55, v35, v59
	v_add_f32_e32 v35, v40, v48
	v_mul_f32_e32 v35, 0xbfb8aa3b, v35
	v_exp_f32_e32 v35, v35
	v_mul_f32_e32 v39, 0x42000000, v55
	v_med3_f32 v39, v39, s29, v231
	v_add_f32_e32 v10, 1.0, v10
	v_add_f32_e32 v35, 1.0, v35
	v_rcp_f32_e32 v35, v35
	v_rcp_f32_e32 v10, v10
	v_mul_f32_e32 v11, 0xbfb8aa3b, v11
	v_exp_f32_e32 v11, v11
	v_mul_f32_e32 v35, v35, v142
	v_add_f32_e32 v40, v35, v35
	v_mul_f32_e32 v40, 0x3fb8aa3b, v40
	v_exp_f32_e32 v40, v40
	v_add_f32_e32 v11, 1.0, v11
	v_rcp_f32_e32 v11, v11
	v_add_f32_e32 v12, v12, v44
	v_sub_f32_e32 v40, 1.0, v40
	v_max_f32_e32 v40, 0, v40
	v_sqrt_f32_e32 v40, v40
	v_mul_f32_e32 v12, 0xbfb8aa3b, v12
	v_exp_f32_e32 v12, v12
	v_add_f32_e32 v6, v6, v30
	v_mul_f32_e32 v36, v36, v40
	v_add_f32_e32 v40, v41, v49
	v_mul_f32_e32 v40, 0xbfb8aa3b, v40
	v_exp_f32_e32 v40, v40
	v_mul_f32_e32 v36, v36, v60
	v_mul_f32_e32 v36, 0x42000000, v36
	v_med3_f32 v36, v36, s29, v231
	v_add_f32_e32 v40, 1.0, v40
	v_rcp_f32_e32 v40, v40
	v_add_f32_e32 v12, 1.0, v12
	v_rcp_f32_e32 v12, v12
	v_add_f32_e32 v13, v13, v45
	v_mul_f32_e32 v40, v40, v143
	v_add_f32_e32 v41, v40, v40
	v_mul_f32_e32 v41, 0x3fb8aa3b, v41
	v_exp_f32_e32 v41, v41
	v_cvt_pk_bf16_f32 v35, v35, v40
	v_med3_f32 v40, v38, s29, v231
	v_mov_b32_e32 v38, 0
	v_sub_f32_e32 v41, 1.0, v41
	v_max_f32_e32 v41, 0, v41
	v_sqrt_f32_e32 v41, v41
	v_cvt_pk_fp8_f32 v38, v40, v39
	v_lshlrev_b32_e32 v39, 16, v57
	v_and_b32_e32 v40, 0xffff0000, v57
	v_mul_f32_e32 v37, v37, v41
	v_add_f32_e32 v41, v22, v22
	v_mul_f32_e32 v41, 0x3fb8aa3b, v41
	v_exp_f32_e32 v41, v41
	v_mul_f32_e32 v37, v37, v54
	v_mul_f32_e32 v37, 0x42000000, v37
	v_med3_f32 v37, v37, s29, v231
	v_sub_f32_e32 v41, 1.0, v41
	v_max_f32_e32 v41, 0, v41
	v_sqrt_f32_e32 v41, v41
	v_cvt_pk_fp8_f32 v38, v36, v37 op_sel:[0,0,1]
	v_lshlrev_b32_e32 v36, 16, v56
	v_and_b32_e32 v37, 0xffff0000, v56
	v_mul_f32_e32 v18, v18, v41
	v_mul_f32_e32 v18, v18, v36
	v_add_f32_e32 v36, v23, v23
	v_mul_f32_e32 v36, 0x3fb8aa3b, v36
	v_exp_f32_e32 v36, v36
	v_mul_f32_e32 v18, 0x42000000, v18
	v_med3_f32 v18, v18, s29, v231
	v_mul_f32_e32 v6, 0xbfb8aa3b, v6
	v_sub_f32_e32 v36, 1.0, v36
	v_max_f32_e32 v36, 0, v36
	v_sqrt_f32_e32 v36, v36
	v_mul_f32_e32 v13, 0xbfb8aa3b, v13
	v_exp_f32_e32 v6, v6
	v_exp_f32_e32 v13, v13
	v_mul_f32_e32 v19, v19, v36
	v_add_f32_e32 v36, v24, v24
	v_mul_f32_e32 v36, 0x3fb8aa3b, v36
	v_exp_f32_e32 v36, v36
	v_mul_f32_e32 v19, v19, v37
	v_mul_f32_e32 v19, 0x42000000, v19
	v_med3_f32 v19, v19, s29, v231
	v_sub_f32_e32 v36, 1.0, v36
	v_max_f32_e32 v36, 0, v36
	v_sqrt_f32_e32 v36, v36
	v_cvt_pk_bf16_f32 v37, v24, v25
	v_add_f32_e32 v6, 1.0, v6
	v_add_f32_e32 v13, 1.0, v13
	v_mul_f32_e32 v20, v20, v36
	v_add_f32_e32 v36, v25, v25
	v_mul_f32_e32 v36, 0x3fb8aa3b, v36
	v_exp_f32_e32 v36, v36
	v_mul_f32_e32 v20, v20, v39
	v_mov_b32_e32 v39, 0
	v_cvt_pk_fp8_f32 v39, v18, v19
	v_sub_f32_e32 v36, 1.0, v36
	v_max_f32_e32 v36, 0, v36
	v_sqrt_f32_e32 v36, v36
	v_mul_f32_e32 v20, 0x42000000, v20
	v_med3_f32 v18, v20, s29, v231
	v_rcp_f32_e32 v6, v6
	v_mul_f32_e32 v21, v21, v36
	v_cvt_pk_bf16_f32 v36, v22, v23
	v_add_f32_e32 v22, v14, v14
	v_mul_f32_e32 v22, 0x3fb8aa3b, v22
	v_exp_f32_e32 v22, v22
	v_mul_f32_e32 v21, v21, v40
	v_mul_f32_e32 v21, 0x42000000, v21
	v_med3_f32 v19, v21, s29, v231
	v_sub_f32_e32 v22, 1.0, v22
	v_max_f32_e32 v22, 0, v22
	v_cvt_pk_fp8_f32 v39, v18, v19 op_sel:[0,0,1]
	v_add_co_u32_e32 v18, vcc, s92, v80
	v_sqrt_f32_e32 v22, v22
	s_nop 0
	v_addc_co_u32_e32 v19, vcc, 0, v81, vcc
	global_store_dwordx4 v[18:19], v[34:37], off nt
	v_add_co_u32_e32 v18, vcc, s84, v78
	v_mul_f32_e32 v10, v10, v22
	s_nop 0
	v_addc_co_u32_e32 v19, vcc, 0, v79, vcc
	global_store_dwordx2 v[18:19], v[38:39], off nt
	v_lshlrev_b32_e32 v18, 16, v50
	v_mul_f32_e32 v18, v10, v18
	v_add_f32_e32 v10, v15, v47
	v_mul_f32_e32 v10, 0xbfb8aa3b, v10
	v_exp_f32_e32 v10, v10
	v_and_b32_e32 v19, 0xffff0000, v50
	v_rcp_f32_e32 v13, v13
	v_mul_f32_e32 v6, v6, v130
	v_add_f32_e32 v10, 1.0, v10
	v_rcp_f32_e32 v10, v10
	v_add_f32_e32 v2, v2, v26
	v_add_f32_e32 v7, v7, v31
	v_mul_f32_e32 v2, 0xbfb8aa3b, v2
	v_mul_f32_e32 v10, v10, v145
	v_add_f32_e32 v15, v10, v10
	v_mul_f32_e32 v15, 0x3fb8aa3b, v15
	v_exp_f32_e32 v15, v15
	v_mul_f32_e32 v7, 0xbfb8aa3b, v7
	v_exp_f32_e32 v2, v2
	v_exp_f32_e32 v7, v7
	v_sub_f32_e32 v15, 1.0, v15
	v_max_f32_e32 v15, 0, v15
	v_sqrt_f32_e32 v15, v15
	v_cvt_pk_bf16_f32 v10, v14, v10
	v_mul_f32_e32 v14, 0x42000000, v18
	v_add_f32_e32 v2, 1.0, v2
	v_mul_f32_e32 v11, v11, v15
	v_mul_f32_e32 v15, v11, v19
	v_add_f32_e32 v11, v16, v48
	v_mul_f32_e32 v11, 0xbfb8aa3b, v11
	v_exp_f32_e32 v11, v11
	v_mul_f32_e32 v15, 0x42000000, v15
	v_med3_f32 v15, v15, s29, v231
	v_add_f32_e32 v7, 1.0, v7
	v_add_f32_e32 v11, 1.0, v11
	v_rcp_f32_e32 v11, v11
	v_lshlrev_b32_e32 v20, 16, v51
	v_and_b32_e32 v21, 0xffff0000, v51
	v_rcp_f32_e32 v2, v2
	v_mul_f32_e32 v11, v11, v142
	v_add_f32_e32 v16, v11, v11
	v_mul_f32_e32 v16, 0x3fb8aa3b, v16
	v_exp_f32_e32 v16, v16
	v_rcp_f32_e32 v7, v7
	v_add_f32_e32 v8, v8, v32
	v_add_f32_e32 v3, v3, v27
	v_sub_f32_e32 v16, 1.0, v16
	v_max_f32_e32 v16, 0, v16
	v_sqrt_f32_e32 v16, v16
	v_mul_f32_e32 v7, v7, v131
	v_mul_f32_e32 v8, 0xbfb8aa3b, v8
	v_mul_f32_e32 v3, 0xbfb8aa3b, v3
	v_mul_f32_e32 v12, v12, v16
	v_add_f32_e32 v16, v17, v49
	v_mul_f32_e32 v16, 0xbfb8aa3b, v16
	v_exp_f32_e32 v16, v16
	v_mul_f32_e32 v12, v12, v20
	v_mul_f32_e32 v12, 0x42000000, v12
	v_med3_f32 v12, v12, s29, v231
	v_add_f32_e32 v16, 1.0, v16
	v_rcp_f32_e32 v16, v16
	v_exp_f32_e32 v8, v8
	v_exp_f32_e32 v3, v3
	v_add_f32_e32 v9, v9, v33
	v_mul_f32_e32 v16, v16, v143
	v_add_f32_e32 v17, v16, v16
	v_mul_f32_e32 v17, 0x3fb8aa3b, v17
	v_exp_f32_e32 v17, v17
	v_cvt_pk_bf16_f32 v11, v11, v16
	v_med3_f32 v16, v14, s29, v231
	v_mov_b32_e32 v14, 0
	v_sub_f32_e32 v17, 1.0, v17
	v_max_f32_e32 v17, 0, v17
	v_sqrt_f32_e32 v17, v17
	v_cvt_pk_fp8_f32 v14, v16, v15
	v_add_f32_e32 v8, 1.0, v8
	v_add_f32_e32 v3, 1.0, v3
	v_mul_f32_e32 v13, v13, v17
	v_add_f32_e32 v17, v6, v6
	v_mul_f32_e32 v17, 0x3fb8aa3b, v17
	v_exp_f32_e32 v17, v17
	v_mul_f32_e32 v13, v13, v21
	v_mul_f32_e32 v13, 0x42000000, v13
	v_med3_f32 v13, v13, s29, v231
	v_sub_f32_e32 v17, 1.0, v17
	v_max_f32_e32 v17, 0, v17
	v_sqrt_f32_e32 v17, v17
	v_cvt_pk_fp8_f32 v14, v12, v13 op_sel:[0,0,1]
	v_lshlrev_b32_e32 v12, 16, v52
	v_rcp_f32_e32 v8, v8
	v_mul_f32_e32 v2, v2, v17
	v_mul_f32_e32 v2, v2, v12
	v_add_f32_e32 v12, v7, v7
	v_mul_f32_e32 v12, 0x3fb8aa3b, v12
	v_exp_f32_e32 v12, v12
	v_rcp_f32_e32 v3, v3
	v_mul_f32_e32 v8, v8, v132
	v_add_f32_e32 v4, v4, v28
	v_sub_f32_e32 v12, 1.0, v12
	v_max_f32_e32 v12, 0, v12
	v_sqrt_f32_e32 v12, v12
	v_mul_f32_e32 v9, 0xbfb8aa3b, v9
	v_mul_f32_e32 v4, 0xbfb8aa3b, v4
	v_exp_f32_e32 v9, v9
	v_mul_f32_e32 v3, v3, v12
	v_add_f32_e32 v12, v8, v8
	v_mul_f32_e32 v12, 0x3fb8aa3b, v12
	v_exp_f32_e32 v12, v12
	v_exp_f32_e32 v4, v4
	v_add_f32_e32 v9, 1.0, v9
	v_rcp_f32_e32 v9, v9
	v_sub_f32_e32 v12, 1.0, v12
	v_add_f32_e32 v4, 1.0, v4
	v_max_f32_e32 v12, 0, v12
	v_rcp_f32_e32 v4, v4
	v_sqrt_f32_e32 v12, v12
	v_mul_f32_e32 v9, v9, v133
	v_add_f32_e32 v5, v5, v29
	v_mul_f32_e32 v5, 0xbfb8aa3b, v5
	v_mul_f32_e32 v4, v4, v12
	v_add_f32_e32 v12, v9, v9
	v_mul_f32_e32 v12, 0x3fb8aa3b, v12
	v_exp_f32_e32 v12, v12
	v_exp_f32_e32 v5, v5
	v_and_b32_e32 v13, 0xffff0000, v52
	v_mul_f32_e32 v3, v3, v13
	v_sub_f32_e32 v12, 1.0, v12
	v_add_f32_e32 v5, 1.0, v5
	v_max_f32_e32 v12, 0, v12
	v_rcp_f32_e32 v5, v5
	v_sqrt_f32_e32 v12, v12
	v_lshlrev_b32_e32 v15, 16, v53
	v_mul_f32_e32 v2, 0x42000000, v2
	v_mul_f32_e32 v3, 0x42000000, v3
	v_mul_f32_e32 v4, v4, v15
	v_med3_f32 v2, v2, s29, v231
	v_med3_f32 v3, v3, s29, v231
	v_mov_b32_e32 v15, 0
	v_and_b32_e32 v16, 0xffff0000, v53
	v_mul_f32_e32 v5, v5, v12
	v_cvt_pk_fp8_f32 v15, v2, v3
	v_mul_f32_e32 v5, v5, v16
	v_mul_f32_e32 v4, 0x42000000, v4
	v_mul_f32_e32 v5, 0x42000000, v5
	v_med3_f32 v2, v4, s29, v231
	v_med3_f32 v3, v5, s29, v231
	v_cvt_pk_fp8_f32 v15, v2, v3 op_sel:[0,0,1]
	v_add_co_u32_e32 v2, vcc, 0x18000, v80
	v_cvt_pk_bf16_f32 v12, v6, v7
	v_cvt_pk_bf16_f32 v13, v8, v9
	v_addc_co_u32_e32 v3, vcc, 0, v81, vcc
	global_store_dwordx4 v[2:3], v[10:13], off nt
	v_add_co_u32_e32 v2, vcc, 0xc000, v78
	s_nop 1
	v_addc_co_u32_e32 v3, vcc, 0, v79, vcc
	global_store_dwordx2 v[2:3], v[14:15], off nt
	s_and_b64 vcc, exec, s[12:13]
	s_mov_b32 s82, s40
	s_mov_b32 s52, s42
	s_mov_b64 s[14:15], s[46:47]
	s_mov_b64 s[48:49], s[44:45]
	s_mov_b32 s94, s23
	s_cbranch_vccz .LBB0_1638
	s_waitcnt vmcnt(0)
	s_cmpk_gt_u32 s22, 0xff
	v_readlane_b32 s81, v253, 46
	v_readlane_b32 s80, v253, 45
	v_readlane_b32 s89, v253, 44
	s_cbranch_scc1 .LBB0_1649
	s_barrier
